# streaming (nt) hint on the f32 residual-stream stores of the P2/P8 epilogues (far reuse), on top of the chained activation-major kernel
# baseline (speedup 1.0000x reference)
; __device__ __forceinline__ unsigned cvt_pk_bf16(float lo, float hi) { unsigned r; asm volatile("v_cvt_pk_bf16_f32 %0, %1, %2" : "=v"(r) : "v"(lo), "v"(hi)); return r; }
;     __device__ __forceinline__ void operator()(const f32x4 (&acc)[2][2][4][2], const Unit& u, int wr, int wc, int fr, int fq) const {
;     ...
;             for (int m = 0; m < 4; ++m) { const size_t r = (size_t)(row0 + ai * HALF + m * 16); const size_t off = r * ldc + col0; float ss = 0.f;
; #pragma unroll
;                 for (int bj = 0; bj < 2; ++bj) { const f32x4 b0 = *(const f32x4*)(base + off + bj * HALF), b1 = *(const f32x4*)(base + off + bj * HALF + 4);
;                     const f32x4 g0 = *(const f32x4*)(gain + col0 + bj * HALF), g1 = *(const f32x4*)(gain + col0 + bj * HALF + 4);
;                     const f32x4 v0 = b0 + acc[ai][bj][m][0] * alpha, v1 = b1 + acc[ai][bj][m][1] * alpha;
;                     *(f32x4*)(out + off + bj * HALF) = v0; *(f32x4*)(out + off + bj * HALF + 4) = v1;
;                     ss += (v0[0] * v0[0] + v0[1] * v0[1]) + (v0[2] * v0[2] + v0[3] * v0[3]) + (v1[0] * v1[0] + v1[1] * v1[1]) + (v1[2] * v1[2] + v1[3] * v1[3]);
;                     const f32x4 x0 = v0 * g0, x1 = v1 * g1;
;                     u32x4 w; w.x = cvt_pk_bf16(x0[0], x0[1]); w.y = cvt_pk_bf16(x0[2], x0[3]); w.z = cvt_pk_bf16(x1[0], x1[1]); w.w = cvt_pk_bf16(x1[2], x1[3]);
;                     *(u32x4*)(XB + off + bj * HALF) = w; }
;                 ss += __shfl_xor(ss, 16); ss += __shfl_xor(ss, 32);
;                 if (fq == 0) SSQ[r * 64 + u.pn * 4 + wc] = ss; }
.LBB0_237:
	v_lshl_add_u32 v138, s52, 8, v143
	v_lshl_or_b32 v136, s12, 8, v144
	v_ashrrev_i32_e32 v139, 31, v138
	v_ashrrev_i32_e32 v137, 31, v136
	v_lshlrev_b64 v[134:135], 12, v[138:139]
	v_lshl_add_u64 v[168:169], v[134:135], 0, v[136:137]
	v_lshlrev_b64 v[170:171], 2, v[168:169]
	v_lshl_add_u64 v[172:173], s[8:9], 0, v[170:171]
	global_load_dwordx4 v[152:155], v[172:173], off
	global_load_dwordx4 v[156:159], v[172:173], off offset:16
	v_lshl_add_u64 v[134:135], v[136:137], 2, s[18:19]
	global_load_dwordx4 v[160:163], v[134:135], off
	global_load_dwordx4 v[164:167], v[134:135], off offset:16
	v_lshl_add_u64 v[174:175], v[168:169], 1, s[20:21]
	v_lshl_add_u64 v[176:177], s[26:27], 0, v[170:171]
	s_lshl_b32 s50, s12, 2
	s_ashr_i32 s51, s50, 31
	s_waitcnt vmcnt(3)
	v_pk_fma_f32 v[128:129], v[128:129], 0.5, v[154:155] op_sel_hi:[1,0,1]
	v_pk_fma_f32 v[126:127], v[126:127], 0.5, v[152:153] op_sel_hi:[1,0,1]
	s_waitcnt vmcnt(2)
	v_pk_fma_f32 v[154:155], v[124:125], 0.5, v[158:159] op_sel_hi:[1,0,1]
	v_pk_fma_f32 v[152:153], v[122:123], 0.5, v[156:157] op_sel_hi:[1,0,1]
	s_waitcnt vmcnt(1)
	v_pk_mul_f32 v[124:125], v[162:163], v[128:129]
	v_pk_mul_f32 v[122:123], v[160:161], v[126:127]
	global_store_dwordx4 v[176:177], v[126:129], off nt
	global_store_dwordx4 v[176:177], v[152:155], off offset:16 nt
	s_waitcnt vmcnt(2)
	v_pk_mul_f32 v[156:157], v[166:167], v[154:155]
	v_pk_mul_f32 v[158:159], v[164:165], v[152:153]
	v_cvt_pk_bf16_f32 v122, v122, v123
	v_cvt_pk_bf16_f32 v123, v124, v125
	s_nop 0
	v_cvt_pk_bf16_f32 v124, v158, v159
	v_cvt_pk_bf16_f32 v125, v156, v157
	global_store_dwordx4 v[174:175], v[122:125], off
	global_load_dwordx4 v[156:159], v[172:173], off offset:512
	global_load_dwordx4 v[160:163], v[172:173], off offset:528
	global_load_dwordx4 v[164:167], v[134:135], off offset:512
	global_load_dwordx4 v[168:171], v[134:135], off offset:528
	v_and_b32_e32 v123, 64, v150
	v_xor_b32_e32 v122, 16, v150
	v_add_u32_e32 v123, 64, v123
	v_xor_b32_e32 v124, 32, v150
	v_cmp_lt_i32_e32 vcc, v122, v123
	v_mul_f32_e32 v125, v129, v129
	v_fmac_f32_e32 v125, v128, v128
	v_cndmask_b32_e32 v122, v150, v122, vcc
	v_cmp_lt_i32_e32 vcc, v124, v123
	v_mul_f32_e32 v129, v155, v155
	v_fmac_f32_e32 v129, v154, v154
	v_cndmask_b32_e32 v123, v150, v124, vcc
	v_mul_f32_e32 v124, v127, v127
	v_mul_f32_e32 v127, v153, v153
	v_fmac_f32_e32 v124, v126, v126
	v_fmac_f32_e32 v127, v152, v152
	v_add_f32_e32 v124, v124, v125
	v_add_f32_e32 v124, v127, v124
	v_add_f32_e32 v126, v129, v124
	v_lshlrev_b32_e32 v122, 2, v122
	s_waitcnt vmcnt(3)
	v_pk_fma_f32 v[120:121], v[120:121], 0.5, v[158:159] op_sel_hi:[1,0,1]
	v_pk_fma_f32 v[118:119], v[118:119], 0.5, v[156:157] op_sel_hi:[1,0,1]
	s_waitcnt vmcnt(2)
	v_pk_fma_f32 v[114:115], v[114:115], 0.5, v[160:161] op_sel_hi:[1,0,1]
	v_mul_f32_e32 v127, v119, v119
	v_mul_f32_e32 v128, v121, v121
	v_pk_fma_f32 v[116:117], v[116:117], 0.5, v[162:163] op_sel_hi:[1,0,1]
	v_mul_f32_e32 v129, v115, v115
	v_fmac_f32_e32 v127, v118, v118
	v_fmac_f32_e32 v128, v120, v120
	global_store_dwordx4 v[176:177], v[118:121], off offset:512 nt
	global_store_dwordx4 v[176:177], v[114:117], off offset:528 nt
	v_mul_f32_e32 v151, v117, v117
	s_waitcnt vmcnt(3)
	v_pk_mul_f32 v[124:125], v[166:167], v[120:121]
	v_fmac_f32_e32 v129, v114, v114
	v_add_f32_e32 v120, v127, v128
	v_fmac_f32_e32 v151, v116, v116
	v_add_f32_e32 v120, v129, v120
	v_add_f32_e32 v120, v151, v120
	v_add_f32_e32 v128, v126, v120
	ds_bpermute_b32 v129, v122, v128
	s_waitcnt vmcnt(2)
	v_pk_mul_f32 v[126:127], v[170:171], v[116:117]
	v_pk_mul_f32 v[120:121], v[168:169], v[114:115]
	v_lshlrev_b32_e32 v116, 2, v123
	v_pk_mul_f32 v[118:119], v[164:165], v[118:119]
	s_waitcnt lgkmcnt(0)
	v_add_f32_e32 v114, v128, v129
	ds_bpermute_b32 v115, v116, v114
	v_cvt_pk_bf16_f32 v118, v118, v119
	v_cvt_pk_bf16_f32 v119, v124, v125
	v_cvt_pk_bf16_f32 v120, v120, v121
	v_cvt_pk_bf16_f32 v121, v126, v127
	global_store_dwordx4 v[174:175], v[118:121], off offset:256
	s_and_saveexec_b64 s[60:61], s[0:1]
	s_cbranch_execz .LBB0_239
	v_lshlrev_b64 v[118:119], 8, v[138:139]
	v_lshl_add_u64 v[118:119], s[38:39], 0, v[118:119]
	v_lshl_add_u64 v[118:119], s[50:51], 2, v[118:119]
	s_lshl_b32 s12, s87, 2
	v_lshl_add_u64 v[118:119], v[118:119], 0, s[12:13]
	s_waitcnt lgkmcnt(0)
	v_add_f32_e32 v114, v114, v115
	global_store_dword v[118:119], v114, off
; __device__ __forceinline__ unsigned cvt_pk_bf16(float lo, float hi) { unsigned r; asm volatile("v_cvt_pk_bf16_f32 %0, %1, %2" : "=v"(r) : "v"(lo), "v"(hi)); return r; }
;     __device__ __forceinline__ void operator()(const f32x4 (&acc)[2][2][4][2], const Unit& u, int wr, int wc, int fr, int fq) const {
;     ...
;             for (int m = 0; m < 4; ++m) { const size_t r = (size_t)(row0 + ai * HALF + m * 16); const size_t off = r * ldc + col0; float ss = 0.f;
; #pragma unroll
;                 for (int bj = 0; bj < 2; ++bj) { const f32x4 b0 = *(const f32x4*)(base + off + bj * HALF), b1 = *(const f32x4*)(base + off + bj * HALF + 4);
;                     const f32x4 g0 = *(const f32x4*)(gain + col0 + bj * HALF), g1 = *(const f32x4*)(gain + col0 + bj * HALF + 4);
;                     const f32x4 v0 = b0 + acc[ai][bj][m][0] * alpha, v1 = b1 + acc[ai][bj][m][1] * alpha;
;                     *(f32x4*)(out + off + bj * HALF) = v0; *(f32x4*)(out + off + bj * HALF + 4) = v1;
;                     ss += (v0[0] * v0[0] + v0[1] * v0[1]) + (v0[2] * v0[2] + v0[3] * v0[3]) + (v1[0] * v1[0] + v1[1] * v1[1]) + (v1[2] * v1[2] + v1[3] * v1[3]);
;                     const f32x4 x0 = v0 * g0, x1 = v1 * g1;
;                     u32x4 w; w.x = cvt_pk_bf16(x0[0], x0[1]); w.y = cvt_pk_bf16(x0[2], x0[3]); w.z = cvt_pk_bf16(x1[0], x1[1]); w.w = cvt_pk_bf16(x1[2], x1[3]);
;                     *(u32x4*)(XB + off + bj * HALF) = w; }
;                 ss += __shfl_xor(ss, 16); ss += __shfl_xor(ss, 32);
;                 if (fq == 0) SSQ[r * 64 + u.pn * 4 + wc] = ss; }
.LBB0_239:
	s_or_b64 exec, exec, s[60:61]
	v_or_b32_e32 v114, 16, v138
	s_waitcnt lgkmcnt(0)
	v_ashrrev_i32_e32 v115, 31, v114
	v_lshlrev_b64 v[118:119], 12, v[114:115]
	v_lshl_add_u64 v[128:129], v[118:119], 0, v[136:137]
	v_lshlrev_b64 v[160:161], 2, v[128:129]
	v_lshl_add_u64 v[162:163], s[8:9], 0, v[160:161]
	global_load_dwordx4 v[118:121], v[162:163], off
	global_load_dwordx4 v[124:127], v[162:163], off offset:16
	global_load_dwordx4 v[152:155], v[134:135], off
	global_load_dwordx4 v[156:159], v[134:135], off offset:16
	v_lshl_add_u64 v[128:129], v[128:129], 1, s[20:21]
	v_lshl_add_u64 v[160:161], s[26:27], 0, v[160:161]
	s_waitcnt vmcnt(3)
	v_pk_fma_f32 v[112:113], v[112:113], 0.5, v[120:121] op_sel_hi:[1,0,1]
	v_pk_fma_f32 v[110:111], v[110:111], 0.5, v[118:119] op_sel_hi:[1,0,1]
	s_waitcnt vmcnt(2)
	v_pk_fma_f32 v[108:109], v[108:109], 0.5, v[126:127] op_sel_hi:[1,0,1]
	v_pk_fma_f32 v[106:107], v[106:107], 0.5, v[124:125] op_sel_hi:[1,0,1]
	s_waitcnt vmcnt(1)
	v_pk_mul_f32 v[120:121], v[154:155], v[112:113]
	v_pk_mul_f32 v[118:119], v[152:153], v[110:111]
	global_store_dwordx4 v[160:161], v[110:113], off nt
	global_store_dwordx4 v[160:161], v[106:109], off offset:16 nt
	s_waitcnt vmcnt(2)
	v_pk_mul_f32 v[124:125], v[158:159], v[108:109]
	v_pk_mul_f32 v[126:127], v[156:157], v[106:107]
	v_cvt_pk_bf16_f32 v118, v118, v119
	v_cvt_pk_bf16_f32 v119, v120, v121
	v_mul_f32_e32 v111, v111, v111
	v_cvt_pk_bf16_f32 v120, v126, v127
	v_cvt_pk_bf16_f32 v121, v124, v125
	global_store_dwordx4 v[128:129], v[118:121], off
	global_load_dwordx4 v[118:121], v[162:163], off offset:512
	s_nop 0
	global_load_dwordx4 v[124:127], v[162:163], off offset:528
	global_load_dwordx4 v[152:155], v[134:135], off offset:512
	global_load_dwordx4 v[156:159], v[134:135], off offset:528
	v_mul_f32_e32 v113, v113, v113
	v_mul_f32_e32 v107, v107, v107
	v_fmac_f32_e32 v111, v110, v110
	v_fmac_f32_e32 v113, v112, v112
	v_mul_f32_e32 v109, v109, v109
	v_fmac_f32_e32 v107, v106, v106
	v_add_f32_e32 v106, v111, v113
	v_fmac_f32_e32 v109, v108, v108
	v_add_f32_e32 v106, v107, v106
	v_add_f32_e32 v106, v109, v106
	s_waitcnt vmcnt(3)
	v_pk_fma_f32 v[104:105], v[104:105], 0.5, v[120:121] op_sel_hi:[1,0,1]
	v_pk_fma_f32 v[102:103], v[102:103], 0.5, v[118:119] op_sel_hi:[1,0,1]
	s_waitcnt vmcnt(2)
	v_pk_fma_f32 v[98:99], v[98:99], 0.5, v[124:125] op_sel_hi:[1,0,1]
	v_mul_f32_e32 v107, v103, v103
	v_mul_f32_e32 v108, v105, v105
	v_pk_fma_f32 v[100:101], v[100:101], 0.5, v[126:127] op_sel_hi:[1,0,1]
	v_mul_f32_e32 v109, v99, v99
	v_fmac_f32_e32 v107, v102, v102
	v_fmac_f32_e32 v108, v104, v104
	v_mul_f32_e32 v110, v101, v101
	v_fmac_f32_e32 v109, v98, v98
	v_add_f32_e32 v107, v107, v108
	v_fmac_f32_e32 v110, v100, v100
	v_add_f32_e32 v107, v109, v107
	v_add_f32_e32 v107, v110, v107
	v_add_f32_e32 v110, v106, v107
	ds_bpermute_b32 v111, v122, v110
	global_store_dwordx4 v[160:161], v[102:105], off offset:512 nt
	global_store_dwordx4 v[160:161], v[98:101], off offset:528 nt
	s_waitcnt vmcnt(2)
	v_pk_mul_f32 v[108:109], v[156:157], v[98:99]
	v_pk_mul_f32 v[102:103], v[152:153], v[102:103]
	v_pk_mul_f32 v[104:105], v[154:155], v[104:105]
	s_waitcnt lgkmcnt(0)
	v_add_f32_e32 v98, v110, v111
	ds_bpermute_b32 v99, v116, v98
	v_pk_mul_f32 v[106:107], v[158:159], v[100:101]
	v_cvt_pk_bf16_f32 v100, v102, v103
	v_cvt_pk_bf16_f32 v101, v104, v105
	v_cvt_pk_bf16_f32 v102, v108, v109
	s_nop 0
	v_cvt_pk_bf16_f32 v103, v106, v107
	global_store_dwordx4 v[128:129], v[100:103], off offset:256
	s_and_saveexec_b64 s[60:61], s[0:1]
	s_cbranch_execz .LBB0_241
	v_lshlrev_b64 v[100:101], 8, v[114:115]
	v_lshl_add_u64 v[100:101], s[38:39], 0, v[100:101]
	v_lshl_add_u64 v[100:101], s[50:51], 2, v[100:101]
	s_lshl_b32 s12, s87, 2
	v_lshl_add_u64 v[100:101], v[100:101], 0, s[12:13]
	s_waitcnt lgkmcnt(0)
	v_add_f32_e32 v98, v98, v99
	global_store_dword v[100:101], v98, off
.LBB0_241:
	s_or_b64 exec, exec, s[60:61]
	v_or_b32_e32 v98, 32, v138
	s_waitcnt lgkmcnt(0)
	v_ashrrev_i32_e32 v99, 31, v98
	v_lshlrev_b64 v[100:101], 12, v[98:99]
	v_lshl_add_u64 v[118:119], v[100:101], 0, v[136:137]
	v_lshlrev_b64 v[120:121], 2, v[118:119]
	v_lshl_add_u64 v[124:125], s[8:9], 0, v[120:121]
	global_load_dwordx4 v[100:103], v[124:125], off
	global_load_dwordx4 v[104:107], v[124:125], off offset:16
	global_load_dwordx4 v[108:111], v[134:135], off
	global_load_dwordx4 v[112:115], v[134:135], off offset:16
	v_lshl_add_u64 v[118:119], v[118:119], 1, s[20:21]
	v_lshl_add_u64 v[120:121], s[26:27], 0, v[120:121]
	s_waitcnt vmcnt(3)
	v_pk_fma_f32 v[96:97], v[96:97], 0.5, v[102:103] op_sel_hi:[1,0,1]
	v_pk_fma_f32 v[94:95], v[94:95], 0.5, v[100:101] op_sel_hi:[1,0,1]
	s_waitcnt vmcnt(2)
	v_pk_fma_f32 v[92:93], v[92:93], 0.5, v[106:107] op_sel_hi:[1,0,1]
	v_pk_fma_f32 v[90:91], v[90:91], 0.5, v[104:105] op_sel_hi:[1,0,1]
	s_waitcnt vmcnt(1)
	v_pk_mul_f32 v[102:103], v[110:111], v[96:97]
	v_pk_mul_f32 v[100:101], v[108:109], v[94:95]
	global_store_dwordx4 v[120:121], v[94:97], off nt
	global_store_dwordx4 v[120:121], v[90:93], off offset:16 nt
	s_waitcnt vmcnt(2)
	v_pk_mul_f32 v[104:105], v[114:115], v[92:93]
	v_pk_mul_f32 v[106:107], v[112:113], v[90:91]
	v_cvt_pk_bf16_f32 v100, v100, v101
	v_cvt_pk_bf16_f32 v101, v102, v103
	v_mul_f32_e32 v95, v95, v95
	v_cvt_pk_bf16_f32 v102, v106, v107
	v_cvt_pk_bf16_f32 v103, v104, v105
	global_store_dwordx4 v[118:119], v[100:103], off
	global_load_dwordx4 v[100:103], v[124:125], off offset:512
	s_nop 0
	global_load_dwordx4 v[104:107], v[124:125], off offset:528
	global_load_dwordx4 v[108:111], v[134:135], off offset:512
	global_load_dwordx4 v[112:115], v[134:135], off offset:528
	v_mul_f32_e32 v97, v97, v97
	v_mul_f32_e32 v91, v91, v91
	v_fmac_f32_e32 v95, v94, v94
	v_fmac_f32_e32 v97, v96, v96
	v_mul_f32_e32 v93, v93, v93
	v_fmac_f32_e32 v91, v90, v90
	v_add_f32_e32 v90, v95, v97
	v_fmac_f32_e32 v93, v92, v92
	v_add_f32_e32 v90, v91, v90
	v_add_f32_e32 v90, v93, v90
	s_waitcnt vmcnt(3)
; __device__ __forceinline__ unsigned cvt_pk_bf16(float lo, float hi) { unsigned r; asm volatile("v_cvt_pk_bf16_f32 %0, %1, %2" : "=v"(r) : "v"(lo), "v"(hi)); return r; }
;     __device__ __forceinline__ void operator()(const f32x4 (&acc)[2][2][4][2], const Unit& u, int wr, int wc, int fr, int fq) const {
;     ...
;             for (int m = 0; m < 4; ++m) { const size_t r = (size_t)(row0 + ai * HALF + m * 16); const size_t off = r * ldc + col0; float ss = 0.f;
; #pragma unroll
;                 for (int bj = 0; bj < 2; ++bj) { const f32x4 b0 = *(const f32x4*)(base + off + bj * HALF), b1 = *(const f32x4*)(base + off + bj * HALF + 4);
;                     const f32x4 g0 = *(const f32x4*)(gain + col0 + bj * HALF), g1 = *(const f32x4*)(gain + col0 + bj * HALF + 4);
;                     const f32x4 v0 = b0 + acc[ai][bj][m][0] * alpha, v1 = b1 + acc[ai][bj][m][1] * alpha;
;                     *(f32x4*)(out + off + bj * HALF) = v0; *(f32x4*)(out + off + bj * HALF + 4) = v1;
;                     ss += (v0[0] * v0[0] + v0[1] * v0[1]) + (v0[2] * v0[2] + v0[3] * v0[3]) + (v1[0] * v1[0] + v1[1] * v1[1]) + (v1[2] * v1[2] + v1[3] * v1[3]);
;                     const f32x4 x0 = v0 * g0, x1 = v1 * g1;
;                     u32x4 w; w.x = cvt_pk_bf16(x0[0], x0[1]); w.y = cvt_pk_bf16(x0[2], x0[3]); w.z = cvt_pk_bf16(x1[0], x1[1]); w.w = cvt_pk_bf16(x1[2], x1[3]);
;                     *(u32x4*)(XB + off + bj * HALF) = w; }
;                 ss += __shfl_xor(ss, 16); ss += __shfl_xor(ss, 32);
;                 if (fq == 0) SSQ[r * 64 + u.pn * 4 + wc] = ss; }
	v_pk_fma_f32 v[88:89], v[88:89], 0.5, v[102:103] op_sel_hi:[1,0,1]
	v_pk_fma_f32 v[86:87], v[86:87], 0.5, v[100:101] op_sel_hi:[1,0,1]
	s_waitcnt vmcnt(2)
	v_pk_fma_f32 v[82:83], v[82:83], 0.5, v[104:105] op_sel_hi:[1,0,1]
	v_mul_f32_e32 v91, v87, v87
	v_mul_f32_e32 v92, v89, v89
	v_pk_fma_f32 v[84:85], v[84:85], 0.5, v[106:107] op_sel_hi:[1,0,1]
	v_mul_f32_e32 v93, v83, v83
	v_fmac_f32_e32 v91, v86, v86
	v_fmac_f32_e32 v92, v88, v88
	v_mul_f32_e32 v94, v85, v85
	v_fmac_f32_e32 v93, v82, v82
	v_add_f32_e32 v91, v91, v92
	v_fmac_f32_e32 v94, v84, v84
	v_add_f32_e32 v91, v93, v91
	v_add_f32_e32 v91, v94, v91
	v_add_f32_e32 v94, v90, v91
	ds_bpermute_b32 v95, v122, v94
	global_store_dwordx4 v[120:121], v[86:89], off offset:512 nt
	global_store_dwordx4 v[120:121], v[82:85], off offset:528 nt
	s_waitcnt vmcnt(2)
	v_pk_mul_f32 v[92:93], v[112:113], v[82:83]
	v_pk_mul_f32 v[86:87], v[108:109], v[86:87]
	v_pk_mul_f32 v[88:89], v[110:111], v[88:89]
	s_waitcnt lgkmcnt(0)
	v_add_f32_e32 v82, v94, v95
	ds_bpermute_b32 v83, v116, v82
	v_pk_mul_f32 v[90:91], v[114:115], v[84:85]
	v_cvt_pk_bf16_f32 v84, v86, v87
	v_cvt_pk_bf16_f32 v85, v88, v89
	v_cvt_pk_bf16_f32 v86, v92, v93
	s_nop 0
	v_cvt_pk_bf16_f32 v87, v90, v91
	global_store_dwordx4 v[118:119], v[84:87], off offset:256
	s_and_saveexec_b64 s[60:61], s[0:1]
	s_cbranch_execz .LBB0_243
	v_lshlrev_b64 v[84:85], 8, v[98:99]
	v_lshl_add_u64 v[84:85], s[38:39], 0, v[84:85]
	v_lshl_add_u64 v[84:85], s[50:51], 2, v[84:85]
	s_lshl_b32 s12, s87, 2
	v_lshl_add_u64 v[84:85], v[84:85], 0, s[12:13]
	s_waitcnt lgkmcnt(0)
	v_add_f32_e32 v82, v82, v83
	global_store_dword v[84:85], v82, off
.LBB0_243:
	s_or_b64 exec, exec, s[60:61]
	v_or_b32_e32 v82, 48, v138
	s_waitcnt lgkmcnt(0)
	v_ashrrev_i32_e32 v83, 31, v82
	v_lshlrev_b64 v[84:85], 12, v[82:83]
	v_lshl_add_u64 v[100:101], v[84:85], 0, v[136:137]
	v_lshlrev_b64 v[102:103], 2, v[100:101]
	v_lshl_add_u64 v[104:105], s[8:9], 0, v[102:103]
	global_load_dwordx4 v[84:87], v[104:105], off
	global_load_dwordx4 v[88:91], v[104:105], off offset:16
	global_load_dwordx4 v[92:95], v[134:135], off
	global_load_dwordx4 v[96:99], v[134:135], off offset:16
	v_lshl_add_u64 v[100:101], v[100:101], 1, s[20:21]
	v_lshl_add_u64 v[102:103], s[26:27], 0, v[102:103]
	s_waitcnt vmcnt(3)
	v_pk_fma_f32 v[80:81], v[80:81], 0.5, v[86:87] op_sel_hi:[1,0,1]
	v_pk_fma_f32 v[78:79], v[78:79], 0.5, v[84:85] op_sel_hi:[1,0,1]
	s_waitcnt vmcnt(2)
	v_pk_fma_f32 v[76:77], v[76:77], 0.5, v[90:91] op_sel_hi:[1,0,1]
	v_pk_fma_f32 v[74:75], v[74:75], 0.5, v[88:89] op_sel_hi:[1,0,1]
	s_waitcnt vmcnt(1)
	v_pk_mul_f32 v[86:87], v[94:95], v[80:81]
	v_pk_mul_f32 v[84:85], v[92:93], v[78:79]
	global_store_dwordx4 v[102:103], v[78:81], off nt
	global_store_dwordx4 v[102:103], v[74:77], off offset:16 nt
	s_waitcnt vmcnt(2)
	v_pk_mul_f32 v[88:89], v[98:99], v[76:77]
	v_pk_mul_f32 v[90:91], v[96:97], v[74:75]
	v_cvt_pk_bf16_f32 v84, v84, v85
	v_cvt_pk_bf16_f32 v85, v86, v87
	v_mul_f32_e32 v79, v79, v79
	v_cvt_pk_bf16_f32 v86, v90, v91
	v_cvt_pk_bf16_f32 v87, v88, v89
	global_store_dwordx4 v[100:101], v[84:87], off
	global_load_dwordx4 v[84:87], v[104:105], off offset:512
	s_nop 0
	global_load_dwordx4 v[88:91], v[104:105], off offset:528
	global_load_dwordx4 v[92:95], v[134:135], off offset:512
	global_load_dwordx4 v[96:99], v[134:135], off offset:528
	v_mul_f32_e32 v81, v81, v81
	v_mul_f32_e32 v75, v75, v75
	v_fmac_f32_e32 v79, v78, v78
	v_fmac_f32_e32 v81, v80, v80
	v_mul_f32_e32 v77, v77, v77
	v_fmac_f32_e32 v75, v74, v74
	v_add_f32_e32 v74, v79, v81
	v_fmac_f32_e32 v77, v76, v76
	v_add_f32_e32 v74, v75, v74
	v_add_f32_e32 v74, v77, v74
	s_waitcnt vmcnt(3)
	v_pk_fma_f32 v[72:73], v[72:73], 0.5, v[86:87] op_sel_hi:[1,0,1]
	v_pk_fma_f32 v[70:71], v[70:71], 0.5, v[84:85] op_sel_hi:[1,0,1]
	s_waitcnt vmcnt(2)
	v_pk_fma_f32 v[66:67], v[66:67], 0.5, v[88:89] op_sel_hi:[1,0,1]
	v_mul_f32_e32 v75, v71, v71
	v_mul_f32_e32 v76, v73, v73
	v_pk_fma_f32 v[68:69], v[68:69], 0.5, v[90:91] op_sel_hi:[1,0,1]
	v_mul_f32_e32 v77, v67, v67
	v_fmac_f32_e32 v75, v70, v70
	v_fmac_f32_e32 v76, v72, v72
	v_mul_f32_e32 v78, v69, v69
	v_fmac_f32_e32 v77, v66, v66
	v_add_f32_e32 v75, v75, v76
	v_fmac_f32_e32 v78, v68, v68
	v_add_f32_e32 v75, v77, v75
	v_add_f32_e32 v75, v78, v75
	v_add_f32_e32 v78, v74, v75
	ds_bpermute_b32 v79, v122, v78
	global_store_dwordx4 v[102:103], v[70:73], off offset:512 nt
	global_store_dwordx4 v[102:103], v[66:69], off offset:528 nt
	s_waitcnt vmcnt(2)
	v_pk_mul_f32 v[76:77], v[96:97], v[66:67]
	v_pk_mul_f32 v[70:71], v[92:93], v[70:71]
	v_pk_mul_f32 v[72:73], v[94:95], v[72:73]
	s_waitcnt lgkmcnt(0)
	v_add_f32_e32 v66, v78, v79
	ds_bpermute_b32 v67, v116, v66
	v_pk_mul_f32 v[74:75], v[98:99], v[68:69]
	v_cvt_pk_bf16_f32 v68, v70, v71
	v_cvt_pk_bf16_f32 v69, v72, v73
	v_cvt_pk_bf16_f32 v70, v76, v77
	s_nop 0
	v_cvt_pk_bf16_f32 v71, v74, v75
	global_store_dwordx4 v[100:101], v[68:71], off offset:256
	s_and_saveexec_b64 s[60:61], s[0:1]
	s_cbranch_execz .LBB0_245
	v_lshlrev_b64 v[68:69], 8, v[82:83]
	v_lshl_add_u64 v[68:69], s[38:39], 0, v[68:69]
	v_lshl_add_u64 v[68:69], s[50:51], 2, v[68:69]
	s_lshl_b32 s12, s87, 2
	v_lshl_add_u64 v[68:69], v[68:69], 0, s[12:13]
	s_waitcnt lgkmcnt(0)
	v_add_f32_e32 v66, v66, v67
	global_store_dword v[68:69], v66, off
; __device__ __forceinline__ unsigned cvt_pk_bf16(float lo, float hi) { unsigned r; asm volatile("v_cvt_pk_bf16_f32 %0, %1, %2" : "=v"(r) : "v"(lo), "v"(hi)); return r; }
;     __device__ __forceinline__ void operator()(const f32x4 (&acc)[2][2][4][2], const Unit& u, int wr, int wc, int fr, int fq) const {
;     ...
;             for (int m = 0; m < 4; ++m) { const size_t r = (size_t)(row0 + ai * HALF + m * 16); const size_t off = r * ldc + col0; float ss = 0.f;
; #pragma unroll
;                 for (int bj = 0; bj < 2; ++bj) { const f32x4 b0 = *(const f32x4*)(base + off + bj * HALF), b1 = *(const f32x4*)(base + off + bj * HALF + 4);
;                     const f32x4 g0 = *(const f32x4*)(gain + col0 + bj * HALF), g1 = *(const f32x4*)(gain + col0 + bj * HALF + 4);
;                     const f32x4 v0 = b0 + acc[ai][bj][m][0] * alpha, v1 = b1 + acc[ai][bj][m][1] * alpha;
;                     *(f32x4*)(out + off + bj * HALF) = v0; *(f32x4*)(out + off + bj * HALF + 4) = v1;
;                     ss += (v0[0] * v0[0] + v0[1] * v0[1]) + (v0[2] * v0[2] + v0[3] * v0[3]) + (v1[0] * v1[0] + v1[1] * v1[1]) + (v1[2] * v1[2] + v1[3] * v1[3]);
;                     const f32x4 x0 = v0 * g0, x1 = v1 * g1;
;                     u32x4 w; w.x = cvt_pk_bf16(x0[0], x0[1]); w.y = cvt_pk_bf16(x0[2], x0[3]); w.z = cvt_pk_bf16(x1[0], x1[1]); w.w = cvt_pk_bf16(x1[2], x1[3]);
;                     *(u32x4*)(XB + off + bj * HALF) = w; }
;                 ss += __shfl_xor(ss, 16); ss += __shfl_xor(ss, 32);
;                 if (fq == 0) SSQ[r * 64 + u.pn * 4 + wc] = ss; }
.LBB0_245:
	s_or_b64 exec, exec, s[60:61]
	v_add_u32_e32 v66, 0x80, v138
	s_waitcnt lgkmcnt(0)
	v_ashrrev_i32_e32 v67, 31, v66
	v_lshlrev_b64 v[68:69], 12, v[66:67]
	v_lshl_add_u64 v[84:85], v[68:69], 0, v[136:137]
	v_lshlrev_b64 v[86:87], 2, v[84:85]
	v_lshl_add_u64 v[88:89], s[8:9], 0, v[86:87]
	global_load_dwordx4 v[68:71], v[88:89], off
	global_load_dwordx4 v[72:75], v[88:89], off offset:16
	global_load_dwordx4 v[76:79], v[134:135], off
	global_load_dwordx4 v[80:83], v[134:135], off offset:16
	v_lshl_add_u64 v[84:85], v[84:85], 1, s[20:21]
	v_lshl_add_u64 v[86:87], s[26:27], 0, v[86:87]
	s_waitcnt vmcnt(3)
	v_pk_fma_f32 v[64:65], v[64:65], 0.5, v[70:71] op_sel_hi:[1,0,1]
	v_pk_fma_f32 v[62:63], v[62:63], 0.5, v[68:69] op_sel_hi:[1,0,1]
	s_waitcnt vmcnt(2)
	v_pk_fma_f32 v[60:61], v[60:61], 0.5, v[74:75] op_sel_hi:[1,0,1]
	v_pk_fma_f32 v[58:59], v[58:59], 0.5, v[72:73] op_sel_hi:[1,0,1]
	s_waitcnt vmcnt(1)
	v_pk_mul_f32 v[70:71], v[78:79], v[64:65]
	v_pk_mul_f32 v[68:69], v[76:77], v[62:63]
	global_store_dwordx4 v[86:87], v[62:65], off nt
	global_store_dwordx4 v[86:87], v[58:61], off offset:16 nt
	s_waitcnt vmcnt(2)
	v_pk_mul_f32 v[72:73], v[82:83], v[60:61]
	v_pk_mul_f32 v[74:75], v[80:81], v[58:59]
	v_cvt_pk_bf16_f32 v68, v68, v69
	v_cvt_pk_bf16_f32 v69, v70, v71
	v_mul_f32_e32 v63, v63, v63
	v_cvt_pk_bf16_f32 v70, v74, v75
	v_cvt_pk_bf16_f32 v71, v72, v73
	global_store_dwordx4 v[84:85], v[68:71], off
	global_load_dwordx4 v[68:71], v[88:89], off offset:512
	s_nop 0
	global_load_dwordx4 v[72:75], v[88:89], off offset:528
	global_load_dwordx4 v[76:79], v[134:135], off offset:512
	global_load_dwordx4 v[80:83], v[134:135], off offset:528
	v_mul_f32_e32 v65, v65, v65
	v_mul_f32_e32 v59, v59, v59
	v_fmac_f32_e32 v63, v62, v62
	v_fmac_f32_e32 v65, v64, v64
	v_mul_f32_e32 v61, v61, v61
	v_fmac_f32_e32 v59, v58, v58
	v_add_f32_e32 v58, v63, v65
	v_fmac_f32_e32 v61, v60, v60
	v_add_f32_e32 v58, v59, v58
	v_add_f32_e32 v58, v61, v58
	s_waitcnt vmcnt(3)
	v_pk_fma_f32 v[56:57], v[56:57], 0.5, v[70:71] op_sel_hi:[1,0,1]
	v_pk_fma_f32 v[54:55], v[54:55], 0.5, v[68:69] op_sel_hi:[1,0,1]
	s_waitcnt vmcnt(2)
	v_pk_fma_f32 v[50:51], v[50:51], 0.5, v[72:73] op_sel_hi:[1,0,1]
	v_mul_f32_e32 v59, v55, v55
	v_mul_f32_e32 v60, v57, v57
	v_pk_fma_f32 v[52:53], v[52:53], 0.5, v[74:75] op_sel_hi:[1,0,1]
	v_mul_f32_e32 v61, v51, v51
	v_fmac_f32_e32 v59, v54, v54
	v_fmac_f32_e32 v60, v56, v56
	v_mul_f32_e32 v62, v53, v53
	v_fmac_f32_e32 v61, v50, v50
	v_add_f32_e32 v59, v59, v60
	v_fmac_f32_e32 v62, v52, v52
	v_add_f32_e32 v59, v61, v59
	v_add_f32_e32 v59, v62, v59
	v_add_f32_e32 v62, v58, v59
	ds_bpermute_b32 v63, v122, v62
	global_store_dwordx4 v[86:87], v[54:57], off offset:512 nt
	global_store_dwordx4 v[86:87], v[50:53], off offset:528 nt
	s_waitcnt vmcnt(2)
	v_pk_mul_f32 v[60:61], v[80:81], v[50:51]
	v_pk_mul_f32 v[54:55], v[76:77], v[54:55]
	v_pk_mul_f32 v[56:57], v[78:79], v[56:57]
	s_waitcnt lgkmcnt(0)
	v_add_f32_e32 v50, v62, v63
	ds_bpermute_b32 v51, v116, v50
	v_pk_mul_f32 v[58:59], v[82:83], v[52:53]
	v_cvt_pk_bf16_f32 v52, v54, v55
	v_cvt_pk_bf16_f32 v53, v56, v57
	v_cvt_pk_bf16_f32 v54, v60, v61
	s_nop 0
	v_cvt_pk_bf16_f32 v55, v58, v59
	global_store_dwordx4 v[84:85], v[52:55], off offset:256
	s_and_saveexec_b64 s[60:61], s[0:1]
	s_cbranch_execz .LBB0_247
	v_lshlrev_b64 v[52:53], 8, v[66:67]
	v_lshl_add_u64 v[52:53], s[38:39], 0, v[52:53]
	v_lshl_add_u64 v[52:53], s[50:51], 2, v[52:53]
	s_lshl_b32 s12, s87, 2
	v_lshl_add_u64 v[52:53], v[52:53], 0, s[12:13]
	s_waitcnt lgkmcnt(0)
	v_add_f32_e32 v50, v50, v51
	global_store_dword v[52:53], v50, off
.LBB0_247:
	s_or_b64 exec, exec, s[60:61]
	v_add_u32_e32 v50, 0x90, v138
	s_waitcnt lgkmcnt(0)
	v_ashrrev_i32_e32 v51, 31, v50
	v_lshlrev_b64 v[52:53], 12, v[50:51]
	v_lshl_add_u64 v[68:69], v[52:53], 0, v[136:137]
	v_lshlrev_b64 v[70:71], 2, v[68:69]
	v_lshl_add_u64 v[72:73], s[8:9], 0, v[70:71]
	global_load_dwordx4 v[52:55], v[72:73], off
	global_load_dwordx4 v[56:59], v[72:73], off offset:16
	global_load_dwordx4 v[60:63], v[134:135], off
	global_load_dwordx4 v[64:67], v[134:135], off offset:16
	v_lshl_add_u64 v[68:69], v[68:69], 1, s[20:21]
	v_lshl_add_u64 v[70:71], s[26:27], 0, v[70:71]
	s_waitcnt vmcnt(3)
	v_pk_fma_f32 v[48:49], v[48:49], 0.5, v[54:55] op_sel_hi:[1,0,1]
	v_pk_fma_f32 v[46:47], v[46:47], 0.5, v[52:53] op_sel_hi:[1,0,1]
	s_waitcnt vmcnt(2)
	v_pk_fma_f32 v[44:45], v[44:45], 0.5, v[58:59] op_sel_hi:[1,0,1]
	v_pk_fma_f32 v[42:43], v[42:43], 0.5, v[56:57] op_sel_hi:[1,0,1]
	s_waitcnt vmcnt(1)
	v_pk_mul_f32 v[54:55], v[62:63], v[48:49]
	v_pk_mul_f32 v[52:53], v[60:61], v[46:47]
	global_store_dwordx4 v[70:71], v[46:49], off nt
	global_store_dwordx4 v[70:71], v[42:45], off offset:16 nt
	s_waitcnt vmcnt(2)
	v_pk_mul_f32 v[56:57], v[66:67], v[44:45]
	v_pk_mul_f32 v[58:59], v[64:65], v[42:43]
	v_cvt_pk_bf16_f32 v52, v52, v53
	v_cvt_pk_bf16_f32 v53, v54, v55
	v_mul_f32_e32 v47, v47, v47
	v_cvt_pk_bf16_f32 v54, v58, v59
	v_cvt_pk_bf16_f32 v55, v56, v57
	global_store_dwordx4 v[68:69], v[52:55], off
	global_load_dwordx4 v[52:55], v[72:73], off offset:512
	s_nop 0
	global_load_dwordx4 v[56:59], v[72:73], off offset:528
	global_load_dwordx4 v[60:63], v[134:135], off offset:512
	global_load_dwordx4 v[64:67], v[134:135], off offset:528
	v_mul_f32_e32 v49, v49, v49
	v_mul_f32_e32 v43, v43, v43
	v_fmac_f32_e32 v47, v46, v46
	v_fmac_f32_e32 v49, v48, v48
	v_mul_f32_e32 v45, v45, v45
	v_fmac_f32_e32 v43, v42, v42
	v_add_f32_e32 v42, v47, v49
	v_fmac_f32_e32 v45, v44, v44
	v_add_f32_e32 v42, v43, v42
	v_add_f32_e32 v42, v45, v42
	s_waitcnt vmcnt(3)
	v_pk_fma_f32 v[40:41], v[40:41], 0.5, v[54:55] op_sel_hi:[1,0,1]
	v_pk_fma_f32 v[38:39], v[38:39], 0.5, v[52:53] op_sel_hi:[1,0,1]
	s_waitcnt vmcnt(2)
	v_pk_fma_f32 v[34:35], v[34:35], 0.5, v[56:57] op_sel_hi:[1,0,1]
	v_mul_f32_e32 v43, v39, v39
	v_mul_f32_e32 v44, v41, v41
	v_pk_fma_f32 v[36:37], v[36:37], 0.5, v[58:59] op_sel_hi:[1,0,1]
	v_mul_f32_e32 v45, v35, v35
	v_fmac_f32_e32 v43, v38, v38
	v_fmac_f32_e32 v44, v40, v40
	v_mul_f32_e32 v46, v37, v37
	v_fmac_f32_e32 v45, v34, v34
	v_add_f32_e32 v43, v43, v44
	v_fmac_f32_e32 v46, v36, v36
	v_add_f32_e32 v43, v45, v43
	v_add_f32_e32 v43, v46, v43
	v_add_f32_e32 v46, v42, v43
	ds_bpermute_b32 v47, v122, v46
	global_store_dwordx4 v[70:71], v[38:41], off offset:512 nt
	global_store_dwordx4 v[70:71], v[34:37], off offset:528 nt
	s_waitcnt vmcnt(2)
	v_pk_mul_f32 v[44:45], v[64:65], v[34:35]
	v_pk_mul_f32 v[38:39], v[60:61], v[38:39]
	v_pk_mul_f32 v[40:41], v[62:63], v[40:41]
	s_waitcnt lgkmcnt(0)
	v_add_f32_e32 v34, v46, v47
	ds_bpermute_b32 v35, v116, v34
	v_pk_mul_f32 v[42:43], v[66:67], v[36:37]
	v_cvt_pk_bf16_f32 v36, v38, v39
	v_cvt_pk_bf16_f32 v37, v40, v41
	v_cvt_pk_bf16_f32 v38, v44, v45
	s_nop 0
	v_cvt_pk_bf16_f32 v39, v42, v43
	global_store_dwordx4 v[68:69], v[36:39], off offset:256
	s_and_saveexec_b64 s[60:61], s[0:1]
	s_cbranch_execz .LBB0_249
; __device__ __forceinline__ unsigned cvt_pk_bf16(float lo, float hi) { unsigned r; asm volatile("v_cvt_pk_bf16_f32 %0, %1, %2" : "=v"(r) : "v"(lo), "v"(hi)); return r; }
;     __device__ __forceinline__ void operator()(const f32x4 (&acc)[2][2][4][2], const Unit& u, int wr, int wc, int fr, int fq) const {
;     ...
;             for (int m = 0; m < 4; ++m) { const size_t r = (size_t)(row0 + ai * HALF + m * 16); const size_t off = r * ldc + col0; float ss = 0.f;
; #pragma unroll
;                 for (int bj = 0; bj < 2; ++bj) { const f32x4 b0 = *(const f32x4*)(base + off + bj * HALF), b1 = *(const f32x4*)(base + off + bj * HALF + 4);
;                     const f32x4 g0 = *(const f32x4*)(gain + col0 + bj * HALF), g1 = *(const f32x4*)(gain + col0 + bj * HALF + 4);
;                     const f32x4 v0 = b0 + acc[ai][bj][m][0] * alpha, v1 = b1 + acc[ai][bj][m][1] * alpha;
;                     *(f32x4*)(out + off + bj * HALF) = v0; *(f32x4*)(out + off + bj * HALF + 4) = v1;
;                     ss += (v0[0] * v0[0] + v0[1] * v0[1]) + (v0[2] * v0[2] + v0[3] * v0[3]) + (v1[0] * v1[0] + v1[1] * v1[1]) + (v1[2] * v1[2] + v1[3] * v1[3]);
;                     const f32x4 x0 = v0 * g0, x1 = v1 * g1;
;                     u32x4 w; w.x = cvt_pk_bf16(x0[0], x0[1]); w.y = cvt_pk_bf16(x0[2], x0[3]); w.z = cvt_pk_bf16(x1[0], x1[1]); w.w = cvt_pk_bf16(x1[2], x1[3]);
;                     *(u32x4*)(XB + off + bj * HALF) = w; }
;                 ss += __shfl_xor(ss, 16); ss += __shfl_xor(ss, 32);
;                 if (fq == 0) SSQ[r * 64 + u.pn * 4 + wc] = ss; }
	v_lshlrev_b64 v[36:37], 8, v[50:51]
	v_lshl_add_u64 v[36:37], s[38:39], 0, v[36:37]
	v_lshl_add_u64 v[36:37], s[50:51], 2, v[36:37]
	s_lshl_b32 s12, s87, 2
	v_lshl_add_u64 v[36:37], v[36:37], 0, s[12:13]
	s_waitcnt lgkmcnt(0)
	v_add_f32_e32 v34, v34, v35
	global_store_dword v[36:37], v34, off
.LBB0_249:
	s_or_b64 exec, exec, s[60:61]
	v_add_u32_e32 v34, 0xa0, v138
	s_waitcnt lgkmcnt(0)
	v_ashrrev_i32_e32 v35, 31, v34
	v_lshlrev_b64 v[36:37], 12, v[34:35]
	v_lshl_add_u64 v[52:53], v[36:37], 0, v[136:137]
	v_lshlrev_b64 v[54:55], 2, v[52:53]
	v_lshl_add_u64 v[56:57], s[8:9], 0, v[54:55]
	global_load_dwordx4 v[36:39], v[56:57], off
	global_load_dwordx4 v[40:43], v[56:57], off offset:16
	global_load_dwordx4 v[44:47], v[134:135], off
	global_load_dwordx4 v[48:51], v[134:135], off offset:16
	v_lshl_add_u64 v[52:53], v[52:53], 1, s[20:21]
	v_lshl_add_u64 v[54:55], s[26:27], 0, v[54:55]
	s_waitcnt vmcnt(3)
	v_pk_fma_f32 v[32:33], v[32:33], 0.5, v[38:39] op_sel_hi:[1,0,1]
	v_pk_fma_f32 v[30:31], v[30:31], 0.5, v[36:37] op_sel_hi:[1,0,1]
	s_waitcnt vmcnt(2)
	v_pk_fma_f32 v[28:29], v[28:29], 0.5, v[42:43] op_sel_hi:[1,0,1]
	v_pk_fma_f32 v[26:27], v[26:27], 0.5, v[40:41] op_sel_hi:[1,0,1]
	s_waitcnt vmcnt(1)
	v_pk_mul_f32 v[38:39], v[46:47], v[32:33]
	v_pk_mul_f32 v[36:37], v[44:45], v[30:31]
	global_store_dwordx4 v[54:55], v[30:33], off nt
	global_store_dwordx4 v[54:55], v[26:29], off offset:16 nt
	s_waitcnt vmcnt(2)
	v_pk_mul_f32 v[40:41], v[50:51], v[28:29]
	v_pk_mul_f32 v[42:43], v[48:49], v[26:27]
	v_cvt_pk_bf16_f32 v36, v36, v37
	v_cvt_pk_bf16_f32 v37, v38, v39
	v_mul_f32_e32 v31, v31, v31
	v_cvt_pk_bf16_f32 v38, v42, v43
	v_cvt_pk_bf16_f32 v39, v40, v41
	global_store_dwordx4 v[52:53], v[36:39], off
	global_load_dwordx4 v[36:39], v[56:57], off offset:512
	s_nop 0
	global_load_dwordx4 v[40:43], v[56:57], off offset:528
	global_load_dwordx4 v[44:47], v[134:135], off offset:512
	global_load_dwordx4 v[48:51], v[134:135], off offset:528
	v_mul_f32_e32 v33, v33, v33
	v_mul_f32_e32 v27, v27, v27
	v_fmac_f32_e32 v31, v30, v30
	v_fmac_f32_e32 v33, v32, v32
	v_mul_f32_e32 v29, v29, v29
	v_fmac_f32_e32 v27, v26, v26
	v_add_f32_e32 v26, v31, v33
	v_fmac_f32_e32 v29, v28, v28
	v_add_f32_e32 v26, v27, v26
	v_add_f32_e32 v26, v29, v26
	s_waitcnt vmcnt(3)
	v_pk_fma_f32 v[24:25], v[24:25], 0.5, v[38:39] op_sel_hi:[1,0,1]
	v_pk_fma_f32 v[22:23], v[22:23], 0.5, v[36:37] op_sel_hi:[1,0,1]
	s_waitcnt vmcnt(2)
	v_pk_fma_f32 v[18:19], v[18:19], 0.5, v[40:41] op_sel_hi:[1,0,1]
	v_mul_f32_e32 v27, v23, v23
	v_mul_f32_e32 v28, v25, v25
	v_pk_fma_f32 v[20:21], v[20:21], 0.5, v[42:43] op_sel_hi:[1,0,1]
	v_mul_f32_e32 v29, v19, v19
	v_fmac_f32_e32 v27, v22, v22
	v_fmac_f32_e32 v28, v24, v24
	v_mul_f32_e32 v30, v21, v21
	v_fmac_f32_e32 v29, v18, v18
	v_add_f32_e32 v27, v27, v28
	v_fmac_f32_e32 v30, v20, v20
	v_add_f32_e32 v27, v29, v27
	v_add_f32_e32 v27, v30, v27
	v_add_f32_e32 v30, v26, v27
	ds_bpermute_b32 v31, v122, v30
	global_store_dwordx4 v[54:55], v[22:25], off offset:512 nt
	global_store_dwordx4 v[54:55], v[18:21], off offset:528 nt
	s_waitcnt vmcnt(2)
	v_pk_mul_f32 v[28:29], v[48:49], v[18:19]
	v_pk_mul_f32 v[22:23], v[44:45], v[22:23]
	v_pk_mul_f32 v[24:25], v[46:47], v[24:25]
	s_waitcnt lgkmcnt(0)
	v_add_f32_e32 v18, v30, v31
	ds_bpermute_b32 v19, v116, v18
	v_pk_mul_f32 v[26:27], v[50:51], v[20:21]
	v_cvt_pk_bf16_f32 v20, v22, v23
	v_cvt_pk_bf16_f32 v21, v24, v25
	v_cvt_pk_bf16_f32 v22, v28, v29
	s_nop 0
	v_cvt_pk_bf16_f32 v23, v26, v27
	global_store_dwordx4 v[52:53], v[20:23], off offset:256
	s_and_saveexec_b64 s[60:61], s[0:1]
	s_cbranch_execz .LBB0_251
	v_lshlrev_b64 v[20:21], 8, v[34:35]
	v_lshl_add_u64 v[20:21], s[38:39], 0, v[20:21]
	v_lshl_add_u64 v[20:21], s[50:51], 2, v[20:21]
	s_lshl_b32 s12, s87, 2
	v_lshl_add_u64 v[20:21], v[20:21], 0, s[12:13]
	s_waitcnt lgkmcnt(0)
	v_add_f32_e32 v18, v18, v19
	global_store_dword v[20:21], v18, off
; __device__ __forceinline__ unsigned cvt_pk_bf16(float lo, float hi) { unsigned r; asm volatile("v_cvt_pk_bf16_f32 %0, %1, %2" : "=v"(r) : "v"(lo), "v"(hi)); return r; }
;     __device__ __forceinline__ void operator()(const f32x4 (&acc)[2][2][4][2], const Unit& u, int wr, int wc, int fr, int fq) const {
;     ...
;             for (int m = 0; m < 4; ++m) { const size_t r = (size_t)(row0 + ai * HALF + m * 16); const size_t off = r * ldc + col0; float ss = 0.f;
; #pragma unroll
;                 for (int bj = 0; bj < 2; ++bj) { const f32x4 b0 = *(const f32x4*)(base + off + bj * HALF), b1 = *(const f32x4*)(base + off + bj * HALF + 4);
;                     const f32x4 g0 = *(const f32x4*)(gain + col0 + bj * HALF), g1 = *(const f32x4*)(gain + col0 + bj * HALF + 4);
;                     const f32x4 v0 = b0 + acc[ai][bj][m][0] * alpha, v1 = b1 + acc[ai][bj][m][1] * alpha;
;                     *(f32x4*)(out + off + bj * HALF) = v0; *(f32x4*)(out + off + bj * HALF + 4) = v1;
;                     ss += (v0[0] * v0[0] + v0[1] * v0[1]) + (v0[2] * v0[2] + v0[3] * v0[3]) + (v1[0] * v1[0] + v1[1] * v1[1]) + (v1[2] * v1[2] + v1[3] * v1[3]);
;                     const f32x4 x0 = v0 * g0, x1 = v1 * g1;
;                     u32x4 w; w.x = cvt_pk_bf16(x0[0], x0[1]); w.y = cvt_pk_bf16(x0[2], x0[3]); w.z = cvt_pk_bf16(x1[0], x1[1]); w.w = cvt_pk_bf16(x1[2], x1[3]);
;                     *(u32x4*)(XB + off + bj * HALF) = w; }
;                 ss += __shfl_xor(ss, 16); ss += __shfl_xor(ss, 32);
;                 if (fq == 0) SSQ[r * 64 + u.pn * 4 + wc] = ss; }
.LBB0_251:
	s_or_b64 exec, exec, s[60:61]
	v_add_u32_e32 v18, 0xb0, v138
	s_waitcnt lgkmcnt(0)
	v_ashrrev_i32_e32 v19, 31, v18
	v_lshlrev_b64 v[20:21], 12, v[18:19]
	v_lshl_add_u64 v[36:37], v[20:21], 0, v[136:137]
	v_lshlrev_b64 v[38:39], 2, v[36:37]
	v_lshl_add_u64 v[40:41], s[8:9], 0, v[38:39]
	global_load_dwordx4 v[20:23], v[40:41], off
	global_load_dwordx4 v[24:27], v[40:41], off offset:16
	global_load_dwordx4 v[28:31], v[134:135], off
	global_load_dwordx4 v[32:35], v[134:135], off offset:16
	v_lshl_add_u64 v[36:37], v[36:37], 1, s[20:21]
	v_lshl_add_u64 v[38:39], s[26:27], 0, v[38:39]
	s_waitcnt vmcnt(3)
	v_pk_fma_f32 v[16:17], v[16:17], 0.5, v[22:23] op_sel_hi:[1,0,1]
	v_pk_fma_f32 v[14:15], v[14:15], 0.5, v[20:21] op_sel_hi:[1,0,1]
	s_waitcnt vmcnt(2)
	v_pk_fma_f32 v[12:13], v[12:13], 0.5, v[26:27] op_sel_hi:[1,0,1]
	v_pk_fma_f32 v[10:11], v[10:11], 0.5, v[24:25] op_sel_hi:[1,0,1]
	s_waitcnt vmcnt(1)
	v_pk_mul_f32 v[22:23], v[30:31], v[16:17]
	v_pk_mul_f32 v[20:21], v[28:29], v[14:15]
	global_store_dwordx4 v[38:39], v[14:17], off nt
	global_store_dwordx4 v[38:39], v[10:13], off offset:16 nt
	s_waitcnt vmcnt(2)
	v_pk_mul_f32 v[24:25], v[34:35], v[12:13]
	v_pk_mul_f32 v[26:27], v[32:33], v[10:11]
	v_cvt_pk_bf16_f32 v20, v20, v21
	v_cvt_pk_bf16_f32 v21, v22, v23
	v_mul_f32_e32 v15, v15, v15
	v_cvt_pk_bf16_f32 v22, v26, v27
	v_cvt_pk_bf16_f32 v23, v24, v25
	global_store_dwordx4 v[36:37], v[20:23], off
	global_load_dwordx4 v[20:23], v[40:41], off offset:512
	s_nop 0
	global_load_dwordx4 v[24:27], v[40:41], off offset:528
	global_load_dwordx4 v[28:31], v[134:135], off offset:512
	global_load_dwordx4 v[32:35], v[134:135], off offset:528
	v_mul_f32_e32 v17, v17, v17
	v_mul_f32_e32 v11, v11, v11
	v_fmac_f32_e32 v15, v14, v14
	v_fmac_f32_e32 v17, v16, v16
	v_mul_f32_e32 v13, v13, v13
	v_fmac_f32_e32 v11, v10, v10
	v_add_f32_e32 v10, v15, v17
	v_fmac_f32_e32 v13, v12, v12
	v_add_f32_e32 v10, v11, v10
	v_add_f32_e32 v10, v13, v10
	s_waitcnt vmcnt(3)
	v_pk_fma_f32 v[8:9], v[8:9], 0.5, v[22:23] op_sel_hi:[1,0,1]
	v_pk_fma_f32 v[6:7], v[6:7], 0.5, v[20:21] op_sel_hi:[1,0,1]
	s_waitcnt vmcnt(2)
	v_pk_fma_f32 v[2:3], v[2:3], 0.5, v[24:25] op_sel_hi:[1,0,1]
	v_mul_f32_e32 v11, v7, v7
	v_mul_f32_e32 v12, v9, v9
	v_pk_fma_f32 v[4:5], v[4:5], 0.5, v[26:27] op_sel_hi:[1,0,1]
	v_mul_f32_e32 v13, v3, v3
	v_fmac_f32_e32 v11, v6, v6
	v_fmac_f32_e32 v12, v8, v8
	v_mul_f32_e32 v14, v5, v5
	v_fmac_f32_e32 v13, v2, v2
	v_add_f32_e32 v11, v11, v12
	v_fmac_f32_e32 v14, v4, v4
	v_add_f32_e32 v11, v13, v11
	v_add_f32_e32 v11, v14, v11
	v_add_f32_e32 v14, v10, v11
	ds_bpermute_b32 v15, v122, v14
	global_store_dwordx4 v[38:39], v[6:9], off offset:512 nt
	global_store_dwordx4 v[38:39], v[2:5], off offset:528 nt
	s_waitcnt vmcnt(2)
	v_pk_mul_f32 v[12:13], v[32:33], v[2:3]
	v_pk_mul_f32 v[6:7], v[28:29], v[6:7]
	v_pk_mul_f32 v[8:9], v[30:31], v[8:9]
	s_waitcnt lgkmcnt(0)
	v_add_f32_e32 v2, v14, v15
	ds_bpermute_b32 v3, v116, v2
	v_pk_mul_f32 v[10:11], v[34:35], v[4:5]
	v_cvt_pk_bf16_f32 v4, v6, v7
	v_cvt_pk_bf16_f32 v5, v8, v9
	v_cvt_pk_bf16_f32 v6, v12, v13
	s_nop 0
	v_cvt_pk_bf16_f32 v7, v10, v11
	global_store_dwordx4 v[36:37], v[4:7], off offset:256
	s_and_saveexec_b64 s[60:61], s[0:1]
	s_cbranch_execz .LBB0_253
	v_lshlrev_b64 v[4:5], 8, v[18:19]
	v_lshl_add_u64 v[4:5], s[38:39], 0, v[4:5]
	v_lshl_add_u64 v[4:5], s[50:51], 2, v[4:5]
	s_lshl_b32 s12, s87, 2
	v_lshl_add_u64 v[4:5], v[4:5], 0, s[12:13]
	s_waitcnt lgkmcnt(0)
	v_add_f32_e32 v2, v2, v3
	global_store_dword v[4:5], v2, off

; __device__ __forceinline__ unsigned cvt_pk_bf16(float lo, float hi) { unsigned r; asm volatile("v_cvt_pk_bf16_f32 %0, %1, %2" : "=v"(r) : "v"(lo), "v"(hi)); return r; }
;     __device__ __forceinline__ void operator()(const f32x4 (&acc)[2][2][4][2], const Unit& u, int wr, int wc, int fr, int fq) const {
;     ...
;             for (int m = 0; m < 4; ++m) { const size_t r = (size_t)(row0 + ai * HALF + m * 16); const size_t off = r * ldc + col0; float ss = 0.f;
; #pragma unroll
;                 for (int bj = 0; bj < 2; ++bj) { const f32x4 b0 = *(const f32x4*)(base + off + bj * HALF), b1 = *(const f32x4*)(base + off + bj * HALF + 4);
;                     const f32x4 g0 = *(const f32x4*)(gain + col0 + bj * HALF), g1 = *(const f32x4*)(gain + col0 + bj * HALF + 4);
;                     const f32x4 v0 = b0 + acc[ai][bj][m][0] * alpha, v1 = b1 + acc[ai][bj][m][1] * alpha;
;                     *(f32x4*)(out + off + bj * HALF) = v0; *(f32x4*)(out + off + bj * HALF + 4) = v1;
;                     ss += (v0[0] * v0[0] + v0[1] * v0[1]) + (v0[2] * v0[2] + v0[3] * v0[3]) + (v1[0] * v1[0] + v1[1] * v1[1]) + (v1[2] * v1[2] + v1[3] * v1[3]);
;                     const f32x4 x0 = v0 * g0, x1 = v1 * g1;
;                     u32x4 w; w.x = cvt_pk_bf16(x0[0], x0[1]); w.y = cvt_pk_bf16(x0[2], x0[3]); w.z = cvt_pk_bf16(x1[0], x1[1]); w.w = cvt_pk_bf16(x1[2], x1[3]);
;                     *(u32x4*)(XB + off + bj * HALF) = w; }
;                 ss += __shfl_xor(ss, 16); ss += __shfl_xor(ss, 32);
;                 if (fq == 0) SSQ[r * 64 + u.pn * 4 + wc] = ss; }
.LBB0_701:
	v_lshl_add_u32 v138, s40, 8, v143
	v_lshl_or_b32 v136, s10, 8, v144
	v_ashrrev_i32_e32 v139, 31, v138
	v_ashrrev_i32_e32 v137, 31, v136
	v_lshlrev_b64 v[134:135], 12, v[138:139]
	v_lshl_add_u64 v[168:169], v[134:135], 0, v[136:137]
	v_lshl_add_u64 v[172:173], v[168:169], 2, s[26:27]
	global_load_dwordx4 v[152:155], v[172:173], off
	global_load_dwordx4 v[156:159], v[172:173], off offset:16
	v_lshl_add_u64 v[134:135], v[136:137], 2, s[80:81]
	global_load_dwordx4 v[160:163], v[134:135], off
	global_load_dwordx4 v[164:167], v[134:135], off offset:16
	v_lshl_add_u64 v[174:175], v[168:169], 1, s[20:21]
	s_lshl_b32 s40, s10, 2
	s_ashr_i32 s41, s40, 31
	s_waitcnt vmcnt(3)
	v_pk_add_f32 v[128:129], v[128:129], v[154:155]
	v_pk_add_f32 v[126:127], v[126:127], v[152:153]
	s_waitcnt vmcnt(2)
	v_pk_add_f32 v[154:155], v[124:125], v[158:159]
	v_pk_add_f32 v[152:153], v[122:123], v[156:157]
	s_waitcnt vmcnt(1)
	v_pk_mul_f32 v[124:125], v[162:163], v[128:129]
	v_pk_mul_f32 v[122:123], v[160:161], v[126:127]
	global_store_dwordx4 v[172:173], v[126:129], off nt
	global_store_dwordx4 v[172:173], v[152:155], off offset:16 nt
	s_waitcnt vmcnt(2)
	v_pk_mul_f32 v[156:157], v[166:167], v[154:155]
	v_pk_mul_f32 v[158:159], v[164:165], v[152:153]
	v_cvt_pk_bf16_f32 v122, v122, v123
	v_cvt_pk_bf16_f32 v123, v124, v125
	s_nop 0
	v_cvt_pk_bf16_f32 v124, v158, v159
	v_cvt_pk_bf16_f32 v125, v156, v157
	global_store_dwordx4 v[174:175], v[122:125], off
	global_load_dwordx4 v[156:159], v[172:173], off offset:512
	global_load_dwordx4 v[160:163], v[172:173], off offset:528
	global_load_dwordx4 v[164:167], v[134:135], off offset:512
	global_load_dwordx4 v[168:171], v[134:135], off offset:528
	v_and_b32_e32 v123, 64, v150
	v_xor_b32_e32 v122, 16, v150
	v_add_u32_e32 v123, 64, v123
	v_xor_b32_e32 v124, 32, v150
	v_cmp_lt_i32_e32 vcc, v122, v123
	v_mul_f32_e32 v125, v129, v129
	v_fmac_f32_e32 v125, v128, v128
	v_cndmask_b32_e32 v122, v150, v122, vcc
	v_cmp_lt_i32_e32 vcc, v124, v123
	v_mul_f32_e32 v129, v155, v155
	v_fmac_f32_e32 v129, v154, v154
	v_cndmask_b32_e32 v123, v150, v124, vcc
	v_mul_f32_e32 v124, v127, v127
	v_mul_f32_e32 v127, v153, v153
	v_fmac_f32_e32 v124, v126, v126
	v_fmac_f32_e32 v127, v152, v152
	v_add_f32_e32 v124, v124, v125
	v_add_f32_e32 v124, v127, v124
	v_add_f32_e32 v126, v129, v124
	v_lshlrev_b32_e32 v122, 2, v122
	s_waitcnt vmcnt(3)
	v_pk_add_f32 v[120:121], v[120:121], v[158:159]
	v_pk_add_f32 v[118:119], v[118:119], v[156:157]
	s_waitcnt vmcnt(2)
	v_pk_add_f32 v[114:115], v[114:115], v[160:161]
	v_mul_f32_e32 v127, v119, v119
	v_mul_f32_e32 v128, v121, v121
	v_pk_add_f32 v[116:117], v[116:117], v[162:163]
	v_mul_f32_e32 v129, v115, v115
	v_fmac_f32_e32 v127, v118, v118
	v_fmac_f32_e32 v128, v120, v120
	global_store_dwordx4 v[172:173], v[118:121], off offset:512 nt
	global_store_dwordx4 v[172:173], v[114:117], off offset:528 nt
	v_mul_f32_e32 v151, v117, v117
	s_waitcnt vmcnt(3)
	v_pk_mul_f32 v[124:125], v[166:167], v[120:121]
	v_fmac_f32_e32 v129, v114, v114
	v_add_f32_e32 v120, v127, v128
	v_fmac_f32_e32 v151, v116, v116
	v_add_f32_e32 v120, v129, v120
	v_add_f32_e32 v120, v151, v120
	v_add_f32_e32 v128, v126, v120
	ds_bpermute_b32 v129, v122, v128
	s_waitcnt vmcnt(2)
	v_pk_mul_f32 v[126:127], v[170:171], v[116:117]
	v_pk_mul_f32 v[120:121], v[168:169], v[114:115]
	v_lshlrev_b32_e32 v116, 2, v123
	v_pk_mul_f32 v[118:119], v[164:165], v[118:119]
	s_waitcnt lgkmcnt(0)
	v_add_f32_e32 v114, v128, v129
	ds_bpermute_b32 v115, v116, v114
	v_cvt_pk_bf16_f32 v118, v118, v119
	v_cvt_pk_bf16_f32 v119, v124, v125
	v_cvt_pk_bf16_f32 v120, v120, v121
	v_cvt_pk_bf16_f32 v121, v126, v127
	global_store_dwordx4 v[174:175], v[118:121], off offset:256
	s_and_saveexec_b64 s[42:43], s[0:1]
	s_cbranch_execz .LBB0_703
	v_lshlrev_b64 v[118:119], 8, v[138:139]
	v_lshl_add_u64 v[118:119], s[38:39], 0, v[118:119]
	v_lshl_add_u64 v[118:119], s[40:41], 2, v[118:119]
	s_lshl_b32 s10, s60, 2
	v_lshl_add_u64 v[118:119], v[118:119], 0, s[10:11]
	s_waitcnt lgkmcnt(0)
	v_add_f32_e32 v114, v114, v115
	global_store_dword v[118:119], v114, off
.LBB0_703:
	s_or_b64 exec, exec, s[42:43]
	v_or_b32_e32 v114, 16, v138
	s_waitcnt lgkmcnt(0)
	v_ashrrev_i32_e32 v115, 31, v114
	v_lshlrev_b64 v[118:119], 12, v[114:115]
	v_lshl_add_u64 v[128:129], v[118:119], 0, v[136:137]
	v_lshl_add_u64 v[160:161], v[128:129], 2, s[26:27]
	global_load_dwordx4 v[118:121], v[160:161], off
	global_load_dwordx4 v[124:127], v[160:161], off offset:16
	global_load_dwordx4 v[152:155], v[134:135], off
	global_load_dwordx4 v[156:159], v[134:135], off offset:16
	v_lshl_add_u64 v[128:129], v[128:129], 1, s[20:21]
	s_waitcnt vmcnt(3)
	v_pk_add_f32 v[112:113], v[112:113], v[120:121]
	v_pk_add_f32 v[110:111], v[110:111], v[118:119]
	s_waitcnt vmcnt(2)
	v_pk_add_f32 v[108:109], v[108:109], v[126:127]
	v_pk_add_f32 v[106:107], v[106:107], v[124:125]
	s_waitcnt vmcnt(1)
	v_pk_mul_f32 v[120:121], v[154:155], v[112:113]
	v_pk_mul_f32 v[118:119], v[152:153], v[110:111]
	global_store_dwordx4 v[160:161], v[110:113], off nt
	global_store_dwordx4 v[160:161], v[106:109], off offset:16 nt
	s_waitcnt vmcnt(2)
	v_pk_mul_f32 v[124:125], v[158:159], v[108:109]
	v_pk_mul_f32 v[126:127], v[156:157], v[106:107]
	v_cvt_pk_bf16_f32 v118, v118, v119
	v_cvt_pk_bf16_f32 v119, v120, v121
	v_mul_f32_e32 v111, v111, v111
	v_cvt_pk_bf16_f32 v120, v126, v127
	v_cvt_pk_bf16_f32 v121, v124, v125
	global_store_dwordx4 v[128:129], v[118:121], off
	global_load_dwordx4 v[118:121], v[160:161], off offset:512
	s_nop 0
	global_load_dwordx4 v[124:127], v[160:161], off offset:528
	global_load_dwordx4 v[152:155], v[134:135], off offset:512
	global_load_dwordx4 v[156:159], v[134:135], off offset:528
	v_mul_f32_e32 v113, v113, v113
	v_mul_f32_e32 v107, v107, v107
	v_fmac_f32_e32 v111, v110, v110
	v_fmac_f32_e32 v113, v112, v112
	v_mul_f32_e32 v109, v109, v109
	v_fmac_f32_e32 v107, v106, v106
	v_add_f32_e32 v106, v111, v113
	v_fmac_f32_e32 v109, v108, v108
	v_add_f32_e32 v106, v107, v106
	v_add_f32_e32 v106, v109, v106
	s_waitcnt vmcnt(3)
; __device__ __forceinline__ unsigned cvt_pk_bf16(float lo, float hi) { unsigned r; asm volatile("v_cvt_pk_bf16_f32 %0, %1, %2" : "=v"(r) : "v"(lo), "v"(hi)); return r; }
;     __device__ __forceinline__ void operator()(const f32x4 (&acc)[2][2][4][2], const Unit& u, int wr, int wc, int fr, int fq) const {
;     ...
;             for (int m = 0; m < 4; ++m) { const size_t r = (size_t)(row0 + ai * HALF + m * 16); const size_t off = r * ldc + col0; float ss = 0.f;
; #pragma unroll
;                 for (int bj = 0; bj < 2; ++bj) { const f32x4 b0 = *(const f32x4*)(base + off + bj * HALF), b1 = *(const f32x4*)(base + off + bj * HALF + 4);
;                     const f32x4 g0 = *(const f32x4*)(gain + col0 + bj * HALF), g1 = *(const f32x4*)(gain + col0 + bj * HALF + 4);
;                     const f32x4 v0 = b0 + acc[ai][bj][m][0] * alpha, v1 = b1 + acc[ai][bj][m][1] * alpha;
;                     *(f32x4*)(out + off + bj * HALF) = v0; *(f32x4*)(out + off + bj * HALF + 4) = v1;
;                     ss += (v0[0] * v0[0] + v0[1] * v0[1]) + (v0[2] * v0[2] + v0[3] * v0[3]) + (v1[0] * v1[0] + v1[1] * v1[1]) + (v1[2] * v1[2] + v1[3] * v1[3]);
;                     const f32x4 x0 = v0 * g0, x1 = v1 * g1;
;                     u32x4 w; w.x = cvt_pk_bf16(x0[0], x0[1]); w.y = cvt_pk_bf16(x0[2], x0[3]); w.z = cvt_pk_bf16(x1[0], x1[1]); w.w = cvt_pk_bf16(x1[2], x1[3]);
;                     *(u32x4*)(XB + off + bj * HALF) = w; }
;                 ss += __shfl_xor(ss, 16); ss += __shfl_xor(ss, 32);
;                 if (fq == 0) SSQ[r * 64 + u.pn * 4 + wc] = ss; }
	v_pk_add_f32 v[104:105], v[104:105], v[120:121]
	v_pk_add_f32 v[102:103], v[102:103], v[118:119]
	s_waitcnt vmcnt(2)
	v_pk_add_f32 v[98:99], v[98:99], v[124:125]
	v_mul_f32_e32 v107, v103, v103
	v_mul_f32_e32 v108, v105, v105
	v_pk_add_f32 v[100:101], v[100:101], v[126:127]
	v_mul_f32_e32 v109, v99, v99
	v_fmac_f32_e32 v107, v102, v102
	v_fmac_f32_e32 v108, v104, v104
	v_mul_f32_e32 v110, v101, v101
	v_fmac_f32_e32 v109, v98, v98
	v_add_f32_e32 v107, v107, v108
	v_fmac_f32_e32 v110, v100, v100
	v_add_f32_e32 v107, v109, v107
	v_add_f32_e32 v107, v110, v107
	v_add_f32_e32 v110, v106, v107
	ds_bpermute_b32 v111, v122, v110
	global_store_dwordx4 v[160:161], v[102:105], off offset:512 nt
	global_store_dwordx4 v[160:161], v[98:101], off offset:528 nt
	s_waitcnt vmcnt(2)
	v_pk_mul_f32 v[108:109], v[156:157], v[98:99]
	v_pk_mul_f32 v[102:103], v[152:153], v[102:103]
	v_pk_mul_f32 v[104:105], v[154:155], v[104:105]
	s_waitcnt lgkmcnt(0)
	v_add_f32_e32 v98, v110, v111
	ds_bpermute_b32 v99, v116, v98
	v_pk_mul_f32 v[106:107], v[158:159], v[100:101]
	v_cvt_pk_bf16_f32 v100, v102, v103
	v_cvt_pk_bf16_f32 v101, v104, v105
	v_cvt_pk_bf16_f32 v102, v108, v109
	s_nop 0
	v_cvt_pk_bf16_f32 v103, v106, v107
	global_store_dwordx4 v[128:129], v[100:103], off offset:256
	s_and_saveexec_b64 s[42:43], s[0:1]
	s_cbranch_execz .LBB0_705
	v_lshlrev_b64 v[100:101], 8, v[114:115]
	v_lshl_add_u64 v[100:101], s[38:39], 0, v[100:101]
	v_lshl_add_u64 v[100:101], s[40:41], 2, v[100:101]
	s_lshl_b32 s10, s60, 2
	v_lshl_add_u64 v[100:101], v[100:101], 0, s[10:11]
	s_waitcnt lgkmcnt(0)
	v_add_f32_e32 v98, v98, v99
	global_store_dword v[100:101], v98, off
.LBB0_705:
	s_or_b64 exec, exec, s[42:43]
	v_or_b32_e32 v98, 32, v138
	s_waitcnt lgkmcnt(0)
	v_ashrrev_i32_e32 v99, 31, v98
	v_lshlrev_b64 v[100:101], 12, v[98:99]
	v_lshl_add_u64 v[118:119], v[100:101], 0, v[136:137]
	v_lshl_add_u64 v[120:121], v[118:119], 2, s[26:27]
	global_load_dwordx4 v[100:103], v[120:121], off
	global_load_dwordx4 v[104:107], v[120:121], off offset:16
	global_load_dwordx4 v[108:111], v[134:135], off
	global_load_dwordx4 v[112:115], v[134:135], off offset:16
	v_lshl_add_u64 v[118:119], v[118:119], 1, s[20:21]
	s_waitcnt vmcnt(3)
	v_pk_add_f32 v[96:97], v[96:97], v[102:103]
	v_pk_add_f32 v[94:95], v[94:95], v[100:101]
	s_waitcnt vmcnt(2)
	v_pk_add_f32 v[92:93], v[92:93], v[106:107]
	v_pk_add_f32 v[90:91], v[90:91], v[104:105]
	s_waitcnt vmcnt(1)
	v_pk_mul_f32 v[102:103], v[110:111], v[96:97]
	v_pk_mul_f32 v[100:101], v[108:109], v[94:95]
	global_store_dwordx4 v[120:121], v[94:97], off nt
	global_store_dwordx4 v[120:121], v[90:93], off offset:16 nt
	s_waitcnt vmcnt(2)
	v_pk_mul_f32 v[104:105], v[114:115], v[92:93]
	v_pk_mul_f32 v[106:107], v[112:113], v[90:91]
	v_cvt_pk_bf16_f32 v100, v100, v101
	v_cvt_pk_bf16_f32 v101, v102, v103
	v_mul_f32_e32 v95, v95, v95
	v_cvt_pk_bf16_f32 v102, v106, v107
	v_cvt_pk_bf16_f32 v103, v104, v105
	global_store_dwordx4 v[118:119], v[100:103], off
	global_load_dwordx4 v[100:103], v[120:121], off offset:512
	s_nop 0
	global_load_dwordx4 v[104:107], v[120:121], off offset:528
	global_load_dwordx4 v[108:111], v[134:135], off offset:512
	global_load_dwordx4 v[112:115], v[134:135], off offset:528
	v_mul_f32_e32 v97, v97, v97
	v_mul_f32_e32 v91, v91, v91
	v_fmac_f32_e32 v95, v94, v94
	v_fmac_f32_e32 v97, v96, v96
	v_mul_f32_e32 v93, v93, v93
	v_fmac_f32_e32 v91, v90, v90
	v_add_f32_e32 v90, v95, v97
	v_fmac_f32_e32 v93, v92, v92
	v_add_f32_e32 v90, v91, v90
	v_add_f32_e32 v90, v93, v90
	s_waitcnt vmcnt(3)
	v_pk_add_f32 v[88:89], v[88:89], v[102:103]
	v_pk_add_f32 v[86:87], v[86:87], v[100:101]
	s_waitcnt vmcnt(2)
	v_pk_add_f32 v[82:83], v[82:83], v[104:105]
	v_mul_f32_e32 v91, v87, v87
	v_mul_f32_e32 v92, v89, v89
	v_pk_add_f32 v[84:85], v[84:85], v[106:107]
	v_mul_f32_e32 v93, v83, v83
	v_fmac_f32_e32 v91, v86, v86
	v_fmac_f32_e32 v92, v88, v88
	v_mul_f32_e32 v94, v85, v85
	v_fmac_f32_e32 v93, v82, v82
	v_add_f32_e32 v91, v91, v92
	v_fmac_f32_e32 v94, v84, v84
	v_add_f32_e32 v91, v93, v91
	v_add_f32_e32 v91, v94, v91
	v_add_f32_e32 v94, v90, v91
	ds_bpermute_b32 v95, v122, v94
	global_store_dwordx4 v[120:121], v[86:89], off offset:512 nt
	global_store_dwordx4 v[120:121], v[82:85], off offset:528 nt
	s_waitcnt vmcnt(2)
	v_pk_mul_f32 v[92:93], v[112:113], v[82:83]
	v_pk_mul_f32 v[86:87], v[108:109], v[86:87]
	v_pk_mul_f32 v[88:89], v[110:111], v[88:89]
	s_waitcnt lgkmcnt(0)
	v_add_f32_e32 v82, v94, v95
	ds_bpermute_b32 v83, v116, v82
	v_pk_mul_f32 v[90:91], v[114:115], v[84:85]
	v_cvt_pk_bf16_f32 v84, v86, v87
	v_cvt_pk_bf16_f32 v85, v88, v89
	v_cvt_pk_bf16_f32 v86, v92, v93
	s_nop 0
	v_cvt_pk_bf16_f32 v87, v90, v91
	global_store_dwordx4 v[118:119], v[84:87], off offset:256
	s_and_saveexec_b64 s[42:43], s[0:1]
	s_cbranch_execz .LBB0_707
	v_lshlrev_b64 v[84:85], 8, v[98:99]
	v_lshl_add_u64 v[84:85], s[38:39], 0, v[84:85]
	v_lshl_add_u64 v[84:85], s[40:41], 2, v[84:85]
	s_lshl_b32 s10, s60, 2
	v_lshl_add_u64 v[84:85], v[84:85], 0, s[10:11]
	s_waitcnt lgkmcnt(0)
	v_add_f32_e32 v82, v82, v83
	global_store_dword v[84:85], v82, off
; __device__ __forceinline__ unsigned cvt_pk_bf16(float lo, float hi) { unsigned r; asm volatile("v_cvt_pk_bf16_f32 %0, %1, %2" : "=v"(r) : "v"(lo), "v"(hi)); return r; }
;     __device__ __forceinline__ void operator()(const f32x4 (&acc)[2][2][4][2], const Unit& u, int wr, int wc, int fr, int fq) const {
;     ...
;             for (int m = 0; m < 4; ++m) { const size_t r = (size_t)(row0 + ai * HALF + m * 16); const size_t off = r * ldc + col0; float ss = 0.f;
; #pragma unroll
;                 for (int bj = 0; bj < 2; ++bj) { const f32x4 b0 = *(const f32x4*)(base + off + bj * HALF), b1 = *(const f32x4*)(base + off + bj * HALF + 4);
;                     const f32x4 g0 = *(const f32x4*)(gain + col0 + bj * HALF), g1 = *(const f32x4*)(gain + col0 + bj * HALF + 4);
;                     const f32x4 v0 = b0 + acc[ai][bj][m][0] * alpha, v1 = b1 + acc[ai][bj][m][1] * alpha;
;                     *(f32x4*)(out + off + bj * HALF) = v0; *(f32x4*)(out + off + bj * HALF + 4) = v1;
;                     ss += (v0[0] * v0[0] + v0[1] * v0[1]) + (v0[2] * v0[2] + v0[3] * v0[3]) + (v1[0] * v1[0] + v1[1] * v1[1]) + (v1[2] * v1[2] + v1[3] * v1[3]);
;                     const f32x4 x0 = v0 * g0, x1 = v1 * g1;
;                     u32x4 w; w.x = cvt_pk_bf16(x0[0], x0[1]); w.y = cvt_pk_bf16(x0[2], x0[3]); w.z = cvt_pk_bf16(x1[0], x1[1]); w.w = cvt_pk_bf16(x1[2], x1[3]);
;                     *(u32x4*)(XB + off + bj * HALF) = w; }
;                 ss += __shfl_xor(ss, 16); ss += __shfl_xor(ss, 32);
;                 if (fq == 0) SSQ[r * 64 + u.pn * 4 + wc] = ss; }
.LBB0_707:
	s_or_b64 exec, exec, s[42:43]
	v_or_b32_e32 v82, 48, v138
	s_waitcnt lgkmcnt(0)
	v_ashrrev_i32_e32 v83, 31, v82
	v_lshlrev_b64 v[84:85], 12, v[82:83]
	v_lshl_add_u64 v[100:101], v[84:85], 0, v[136:137]
	v_lshl_add_u64 v[102:103], v[100:101], 2, s[26:27]
	global_load_dwordx4 v[84:87], v[102:103], off
	global_load_dwordx4 v[88:91], v[102:103], off offset:16
	global_load_dwordx4 v[92:95], v[134:135], off
	global_load_dwordx4 v[96:99], v[134:135], off offset:16
	v_lshl_add_u64 v[100:101], v[100:101], 1, s[20:21]
	s_waitcnt vmcnt(3)
	v_pk_add_f32 v[80:81], v[80:81], v[86:87]
	v_pk_add_f32 v[78:79], v[78:79], v[84:85]
	s_waitcnt vmcnt(2)
	v_pk_add_f32 v[76:77], v[76:77], v[90:91]
	v_pk_add_f32 v[74:75], v[74:75], v[88:89]
	s_waitcnt vmcnt(1)
	v_pk_mul_f32 v[86:87], v[94:95], v[80:81]
	v_pk_mul_f32 v[84:85], v[92:93], v[78:79]
	global_store_dwordx4 v[102:103], v[78:81], off nt
	global_store_dwordx4 v[102:103], v[74:77], off offset:16 nt
	s_waitcnt vmcnt(2)
	v_pk_mul_f32 v[88:89], v[98:99], v[76:77]
	v_pk_mul_f32 v[90:91], v[96:97], v[74:75]
	v_cvt_pk_bf16_f32 v84, v84, v85
	v_cvt_pk_bf16_f32 v85, v86, v87
	v_mul_f32_e32 v79, v79, v79
	v_cvt_pk_bf16_f32 v86, v90, v91
	v_cvt_pk_bf16_f32 v87, v88, v89
	global_store_dwordx4 v[100:101], v[84:87], off
	global_load_dwordx4 v[84:87], v[102:103], off offset:512
	s_nop 0
	global_load_dwordx4 v[88:91], v[102:103], off offset:528
	global_load_dwordx4 v[92:95], v[134:135], off offset:512
	global_load_dwordx4 v[96:99], v[134:135], off offset:528
	v_mul_f32_e32 v81, v81, v81
	v_mul_f32_e32 v75, v75, v75
	v_fmac_f32_e32 v79, v78, v78
	v_fmac_f32_e32 v81, v80, v80
	v_mul_f32_e32 v77, v77, v77
	v_fmac_f32_e32 v75, v74, v74
	v_add_f32_e32 v74, v79, v81
	v_fmac_f32_e32 v77, v76, v76
	v_add_f32_e32 v74, v75, v74
	v_add_f32_e32 v74, v77, v74
	s_waitcnt vmcnt(3)
	v_pk_add_f32 v[72:73], v[72:73], v[86:87]
	v_pk_add_f32 v[70:71], v[70:71], v[84:85]
	s_waitcnt vmcnt(2)
	v_pk_add_f32 v[66:67], v[66:67], v[88:89]
	v_mul_f32_e32 v75, v71, v71
	v_mul_f32_e32 v76, v73, v73
	v_pk_add_f32 v[68:69], v[68:69], v[90:91]
	v_mul_f32_e32 v77, v67, v67
	v_fmac_f32_e32 v75, v70, v70
	v_fmac_f32_e32 v76, v72, v72
	v_mul_f32_e32 v78, v69, v69
	v_fmac_f32_e32 v77, v66, v66
	v_add_f32_e32 v75, v75, v76
	v_fmac_f32_e32 v78, v68, v68
	v_add_f32_e32 v75, v77, v75
	v_add_f32_e32 v75, v78, v75
	v_add_f32_e32 v78, v74, v75
	ds_bpermute_b32 v79, v122, v78
	global_store_dwordx4 v[102:103], v[70:73], off offset:512 nt
	global_store_dwordx4 v[102:103], v[66:69], off offset:528 nt
	s_waitcnt vmcnt(2)
	v_pk_mul_f32 v[76:77], v[96:97], v[66:67]
	v_pk_mul_f32 v[70:71], v[92:93], v[70:71]
	v_pk_mul_f32 v[72:73], v[94:95], v[72:73]
	s_waitcnt lgkmcnt(0)
	v_add_f32_e32 v66, v78, v79
	ds_bpermute_b32 v67, v116, v66
	v_pk_mul_f32 v[74:75], v[98:99], v[68:69]
	v_cvt_pk_bf16_f32 v68, v70, v71
	v_cvt_pk_bf16_f32 v69, v72, v73
	v_cvt_pk_bf16_f32 v70, v76, v77
	s_nop 0
	v_cvt_pk_bf16_f32 v71, v74, v75
	global_store_dwordx4 v[100:101], v[68:71], off offset:256
	s_and_saveexec_b64 s[42:43], s[0:1]
	s_cbranch_execz .LBB0_709
	v_lshlrev_b64 v[68:69], 8, v[82:83]
	v_lshl_add_u64 v[68:69], s[38:39], 0, v[68:69]
	v_lshl_add_u64 v[68:69], s[40:41], 2, v[68:69]
	s_lshl_b32 s10, s60, 2
	v_lshl_add_u64 v[68:69], v[68:69], 0, s[10:11]
	s_waitcnt lgkmcnt(0)
	v_add_f32_e32 v66, v66, v67
	global_store_dword v[68:69], v66, off
.LBB0_709:
	s_or_b64 exec, exec, s[42:43]
	v_add_u32_e32 v66, 0x80, v138
	s_waitcnt lgkmcnt(0)
	v_ashrrev_i32_e32 v67, 31, v66
	v_lshlrev_b64 v[68:69], 12, v[66:67]
	v_lshl_add_u64 v[84:85], v[68:69], 0, v[136:137]
	v_lshl_add_u64 v[86:87], v[84:85], 2, s[26:27]
	global_load_dwordx4 v[68:71], v[86:87], off
	global_load_dwordx4 v[72:75], v[86:87], off offset:16
	global_load_dwordx4 v[76:79], v[134:135], off
	global_load_dwordx4 v[80:83], v[134:135], off offset:16
	v_lshl_add_u64 v[84:85], v[84:85], 1, s[20:21]
	s_waitcnt vmcnt(3)
	v_pk_add_f32 v[64:65], v[64:65], v[70:71]
	v_pk_add_f32 v[62:63], v[62:63], v[68:69]
	s_waitcnt vmcnt(2)
	v_pk_add_f32 v[60:61], v[60:61], v[74:75]
	v_pk_add_f32 v[58:59], v[58:59], v[72:73]
	s_waitcnt vmcnt(1)
	v_pk_mul_f32 v[70:71], v[78:79], v[64:65]
	v_pk_mul_f32 v[68:69], v[76:77], v[62:63]
	global_store_dwordx4 v[86:87], v[62:65], off nt
	global_store_dwordx4 v[86:87], v[58:61], off offset:16 nt
	s_waitcnt vmcnt(2)
	v_pk_mul_f32 v[72:73], v[82:83], v[60:61]
	v_pk_mul_f32 v[74:75], v[80:81], v[58:59]
	v_cvt_pk_bf16_f32 v68, v68, v69
	v_cvt_pk_bf16_f32 v69, v70, v71
	v_mul_f32_e32 v63, v63, v63
	v_cvt_pk_bf16_f32 v70, v74, v75
	v_cvt_pk_bf16_f32 v71, v72, v73
	global_store_dwordx4 v[84:85], v[68:71], off
	global_load_dwordx4 v[68:71], v[86:87], off offset:512
	s_nop 0
	global_load_dwordx4 v[72:75], v[86:87], off offset:528
	global_load_dwordx4 v[76:79], v[134:135], off offset:512
	global_load_dwordx4 v[80:83], v[134:135], off offset:528
	v_mul_f32_e32 v65, v65, v65
	v_mul_f32_e32 v59, v59, v59
	v_fmac_f32_e32 v63, v62, v62
	v_fmac_f32_e32 v65, v64, v64
	v_mul_f32_e32 v61, v61, v61
	v_fmac_f32_e32 v59, v58, v58
	v_add_f32_e32 v58, v63, v65
	v_fmac_f32_e32 v61, v60, v60
	v_add_f32_e32 v58, v59, v58
	v_add_f32_e32 v58, v61, v58
	s_waitcnt vmcnt(3)
	v_pk_add_f32 v[56:57], v[56:57], v[70:71]
	v_pk_add_f32 v[54:55], v[54:55], v[68:69]
	s_waitcnt vmcnt(2)
	v_pk_add_f32 v[50:51], v[50:51], v[72:73]
	v_mul_f32_e32 v59, v55, v55
	v_mul_f32_e32 v60, v57, v57
	v_pk_add_f32 v[52:53], v[52:53], v[74:75]
	v_mul_f32_e32 v61, v51, v51
	v_fmac_f32_e32 v59, v54, v54
	v_fmac_f32_e32 v60, v56, v56
	v_mul_f32_e32 v62, v53, v53
	v_fmac_f32_e32 v61, v50, v50
	v_add_f32_e32 v59, v59, v60
	v_fmac_f32_e32 v62, v52, v52
	v_add_f32_e32 v59, v61, v59
	v_add_f32_e32 v59, v62, v59
	v_add_f32_e32 v62, v58, v59
	ds_bpermute_b32 v63, v122, v62
	global_store_dwordx4 v[86:87], v[54:57], off offset:512 nt
	global_store_dwordx4 v[86:87], v[50:53], off offset:528 nt
	s_waitcnt vmcnt(2)
	v_pk_mul_f32 v[60:61], v[80:81], v[50:51]
	v_pk_mul_f32 v[54:55], v[76:77], v[54:55]
	v_pk_mul_f32 v[56:57], v[78:79], v[56:57]
	s_waitcnt lgkmcnt(0)
	v_add_f32_e32 v50, v62, v63
	ds_bpermute_b32 v51, v116, v50
	v_pk_mul_f32 v[58:59], v[82:83], v[52:53]
	v_cvt_pk_bf16_f32 v52, v54, v55
	v_cvt_pk_bf16_f32 v53, v56, v57
	v_cvt_pk_bf16_f32 v54, v60, v61
	s_nop 0
	v_cvt_pk_bf16_f32 v55, v58, v59
	global_store_dwordx4 v[84:85], v[52:55], off offset:256
	s_and_saveexec_b64 s[42:43], s[0:1]
	s_cbranch_execz .LBB0_711
	v_lshlrev_b64 v[52:53], 8, v[66:67]
	v_lshl_add_u64 v[52:53], s[38:39], 0, v[52:53]
	v_lshl_add_u64 v[52:53], s[40:41], 2, v[52:53]
	s_lshl_b32 s10, s60, 2
	v_lshl_add_u64 v[52:53], v[52:53], 0, s[10:11]
	s_waitcnt lgkmcnt(0)
	v_add_f32_e32 v50, v50, v51
	global_store_dword v[52:53], v50, off
; __device__ __forceinline__ unsigned cvt_pk_bf16(float lo, float hi) { unsigned r; asm volatile("v_cvt_pk_bf16_f32 %0, %1, %2" : "=v"(r) : "v"(lo), "v"(hi)); return r; }
;     __device__ __forceinline__ void operator()(const f32x4 (&acc)[2][2][4][2], const Unit& u, int wr, int wc, int fr, int fq) const {
;     ...
;             for (int m = 0; m < 4; ++m) { const size_t r = (size_t)(row0 + ai * HALF + m * 16); const size_t off = r * ldc + col0; float ss = 0.f;
; #pragma unroll
;                 for (int bj = 0; bj < 2; ++bj) { const f32x4 b0 = *(const f32x4*)(base + off + bj * HALF), b1 = *(const f32x4*)(base + off + bj * HALF + 4);
;                     const f32x4 g0 = *(const f32x4*)(gain + col0 + bj * HALF), g1 = *(const f32x4*)(gain + col0 + bj * HALF + 4);
;                     const f32x4 v0 = b0 + acc[ai][bj][m][0] * alpha, v1 = b1 + acc[ai][bj][m][1] * alpha;
;                     *(f32x4*)(out + off + bj * HALF) = v0; *(f32x4*)(out + off + bj * HALF + 4) = v1;
;                     ss += (v0[0] * v0[0] + v0[1] * v0[1]) + (v0[2] * v0[2] + v0[3] * v0[3]) + (v1[0] * v1[0] + v1[1] * v1[1]) + (v1[2] * v1[2] + v1[3] * v1[3]);
;                     const f32x4 x0 = v0 * g0, x1 = v1 * g1;
;                     u32x4 w; w.x = cvt_pk_bf16(x0[0], x0[1]); w.y = cvt_pk_bf16(x0[2], x0[3]); w.z = cvt_pk_bf16(x1[0], x1[1]); w.w = cvt_pk_bf16(x1[2], x1[3]);
;                     *(u32x4*)(XB + off + bj * HALF) = w; }
;                 ss += __shfl_xor(ss, 16); ss += __shfl_xor(ss, 32);
;                 if (fq == 0) SSQ[r * 64 + u.pn * 4 + wc] = ss; }
.LBB0_711:
	s_or_b64 exec, exec, s[42:43]
	v_add_u32_e32 v50, 0x90, v138
	s_waitcnt lgkmcnt(0)
	v_ashrrev_i32_e32 v51, 31, v50
	v_lshlrev_b64 v[52:53], 12, v[50:51]
	v_lshl_add_u64 v[68:69], v[52:53], 0, v[136:137]
	v_lshl_add_u64 v[70:71], v[68:69], 2, s[26:27]
	global_load_dwordx4 v[52:55], v[70:71], off
	global_load_dwordx4 v[56:59], v[70:71], off offset:16
	global_load_dwordx4 v[60:63], v[134:135], off
	global_load_dwordx4 v[64:67], v[134:135], off offset:16
	v_lshl_add_u64 v[68:69], v[68:69], 1, s[20:21]
	s_waitcnt vmcnt(3)
	v_pk_add_f32 v[48:49], v[48:49], v[54:55]
	v_pk_add_f32 v[46:47], v[46:47], v[52:53]
	s_waitcnt vmcnt(2)
	v_pk_add_f32 v[44:45], v[44:45], v[58:59]
	v_pk_add_f32 v[42:43], v[42:43], v[56:57]
	s_waitcnt vmcnt(1)
	v_pk_mul_f32 v[54:55], v[62:63], v[48:49]
	v_pk_mul_f32 v[52:53], v[60:61], v[46:47]
	global_store_dwordx4 v[70:71], v[46:49], off nt
	global_store_dwordx4 v[70:71], v[42:45], off offset:16 nt
	s_waitcnt vmcnt(2)
	v_pk_mul_f32 v[56:57], v[66:67], v[44:45]
	v_pk_mul_f32 v[58:59], v[64:65], v[42:43]
	v_cvt_pk_bf16_f32 v52, v52, v53
	v_cvt_pk_bf16_f32 v53, v54, v55
	v_mul_f32_e32 v47, v47, v47
	v_cvt_pk_bf16_f32 v54, v58, v59
	v_cvt_pk_bf16_f32 v55, v56, v57
	global_store_dwordx4 v[68:69], v[52:55], off
	global_load_dwordx4 v[52:55], v[70:71], off offset:512
	s_nop 0
	global_load_dwordx4 v[56:59], v[70:71], off offset:528
	global_load_dwordx4 v[60:63], v[134:135], off offset:512
	global_load_dwordx4 v[64:67], v[134:135], off offset:528
	v_mul_f32_e32 v49, v49, v49
	v_mul_f32_e32 v43, v43, v43
	v_fmac_f32_e32 v47, v46, v46
	v_fmac_f32_e32 v49, v48, v48
	v_mul_f32_e32 v45, v45, v45
	v_fmac_f32_e32 v43, v42, v42
	v_add_f32_e32 v42, v47, v49
	v_fmac_f32_e32 v45, v44, v44
	v_add_f32_e32 v42, v43, v42
	v_add_f32_e32 v42, v45, v42
	s_waitcnt vmcnt(3)
	v_pk_add_f32 v[40:41], v[40:41], v[54:55]
	v_pk_add_f32 v[38:39], v[38:39], v[52:53]
	s_waitcnt vmcnt(2)
	v_pk_add_f32 v[34:35], v[34:35], v[56:57]
	v_mul_f32_e32 v43, v39, v39
	v_mul_f32_e32 v44, v41, v41
	v_pk_add_f32 v[36:37], v[36:37], v[58:59]
	v_mul_f32_e32 v45, v35, v35
	v_fmac_f32_e32 v43, v38, v38
	v_fmac_f32_e32 v44, v40, v40
	v_mul_f32_e32 v46, v37, v37
	v_fmac_f32_e32 v45, v34, v34
	v_add_f32_e32 v43, v43, v44
	v_fmac_f32_e32 v46, v36, v36
	v_add_f32_e32 v43, v45, v43
	v_add_f32_e32 v43, v46, v43
	v_add_f32_e32 v46, v42, v43
	ds_bpermute_b32 v47, v122, v46
	global_store_dwordx4 v[70:71], v[38:41], off offset:512 nt
	global_store_dwordx4 v[70:71], v[34:37], off offset:528 nt
	s_waitcnt vmcnt(2)
	v_pk_mul_f32 v[44:45], v[64:65], v[34:35]
	v_pk_mul_f32 v[38:39], v[60:61], v[38:39]
	v_pk_mul_f32 v[40:41], v[62:63], v[40:41]
	s_waitcnt lgkmcnt(0)
	v_add_f32_e32 v34, v46, v47
	ds_bpermute_b32 v35, v116, v34
	v_pk_mul_f32 v[42:43], v[66:67], v[36:37]
	v_cvt_pk_bf16_f32 v36, v38, v39
	v_cvt_pk_bf16_f32 v37, v40, v41
	v_cvt_pk_bf16_f32 v38, v44, v45
	s_nop 0
	v_cvt_pk_bf16_f32 v39, v42, v43
	global_store_dwordx4 v[68:69], v[36:39], off offset:256
	s_and_saveexec_b64 s[42:43], s[0:1]
	s_cbranch_execz .LBB0_713
	v_lshlrev_b64 v[36:37], 8, v[50:51]
	v_lshl_add_u64 v[36:37], s[38:39], 0, v[36:37]
	v_lshl_add_u64 v[36:37], s[40:41], 2, v[36:37]
	s_lshl_b32 s10, s60, 2
	v_lshl_add_u64 v[36:37], v[36:37], 0, s[10:11]
	s_waitcnt lgkmcnt(0)
	v_add_f32_e32 v34, v34, v35
	global_store_dword v[36:37], v34, off
; __device__ __forceinline__ unsigned cvt_pk_bf16(float lo, float hi) { unsigned r; asm volatile("v_cvt_pk_bf16_f32 %0, %1, %2" : "=v"(r) : "v"(lo), "v"(hi)); return r; }
;     __device__ __forceinline__ void operator()(const f32x4 (&acc)[2][2][4][2], const Unit& u, int wr, int wc, int fr, int fq) const {
;     ...
;             for (int m = 0; m < 4; ++m) { const size_t r = (size_t)(row0 + ai * HALF + m * 16); const size_t off = r * ldc + col0; float ss = 0.f;
; #pragma unroll
;                 for (int bj = 0; bj < 2; ++bj) { const f32x4 b0 = *(const f32x4*)(base + off + bj * HALF), b1 = *(const f32x4*)(base + off + bj * HALF + 4);
;                     const f32x4 g0 = *(const f32x4*)(gain + col0 + bj * HALF), g1 = *(const f32x4*)(gain + col0 + bj * HALF + 4);
;                     const f32x4 v0 = b0 + acc[ai][bj][m][0] * alpha, v1 = b1 + acc[ai][bj][m][1] * alpha;
;                     *(f32x4*)(out + off + bj * HALF) = v0; *(f32x4*)(out + off + bj * HALF + 4) = v1;
;                     ss += (v0[0] * v0[0] + v0[1] * v0[1]) + (v0[2] * v0[2] + v0[3] * v0[3]) + (v1[0] * v1[0] + v1[1] * v1[1]) + (v1[2] * v1[2] + v1[3] * v1[3]);
;                     const f32x4 x0 = v0 * g0, x1 = v1 * g1;
;                     u32x4 w; w.x = cvt_pk_bf16(x0[0], x0[1]); w.y = cvt_pk_bf16(x0[2], x0[3]); w.z = cvt_pk_bf16(x1[0], x1[1]); w.w = cvt_pk_bf16(x1[2], x1[3]);
;                     *(u32x4*)(XB + off + bj * HALF) = w; }
;                 ss += __shfl_xor(ss, 16); ss += __shfl_xor(ss, 32);
;                 if (fq == 0) SSQ[r * 64 + u.pn * 4 + wc] = ss; }
.LBB0_713:
	s_or_b64 exec, exec, s[42:43]
	v_add_u32_e32 v34, 0xa0, v138
	s_waitcnt lgkmcnt(0)
	v_ashrrev_i32_e32 v35, 31, v34
	v_lshlrev_b64 v[36:37], 12, v[34:35]
	v_lshl_add_u64 v[52:53], v[36:37], 0, v[136:137]
	v_lshl_add_u64 v[54:55], v[52:53], 2, s[26:27]
	global_load_dwordx4 v[36:39], v[54:55], off
	global_load_dwordx4 v[40:43], v[54:55], off offset:16
	global_load_dwordx4 v[44:47], v[134:135], off
	global_load_dwordx4 v[48:51], v[134:135], off offset:16
	v_lshl_add_u64 v[52:53], v[52:53], 1, s[20:21]
	s_waitcnt vmcnt(3)
	v_pk_add_f32 v[32:33], v[32:33], v[38:39]
	v_pk_add_f32 v[30:31], v[30:31], v[36:37]
	s_waitcnt vmcnt(2)
	v_pk_add_f32 v[28:29], v[28:29], v[42:43]
	v_pk_add_f32 v[26:27], v[26:27], v[40:41]
	s_waitcnt vmcnt(1)
	v_pk_mul_f32 v[38:39], v[46:47], v[32:33]
	v_pk_mul_f32 v[36:37], v[44:45], v[30:31]
	global_store_dwordx4 v[54:55], v[30:33], off nt
	global_store_dwordx4 v[54:55], v[26:29], off offset:16 nt
	s_waitcnt vmcnt(2)
	v_pk_mul_f32 v[40:41], v[50:51], v[28:29]
	v_pk_mul_f32 v[42:43], v[48:49], v[26:27]
	v_cvt_pk_bf16_f32 v36, v36, v37
	v_cvt_pk_bf16_f32 v37, v38, v39
	v_mul_f32_e32 v31, v31, v31
	v_cvt_pk_bf16_f32 v38, v42, v43
	v_cvt_pk_bf16_f32 v39, v40, v41
	global_store_dwordx4 v[52:53], v[36:39], off
	global_load_dwordx4 v[36:39], v[54:55], off offset:512
	s_nop 0
	global_load_dwordx4 v[40:43], v[54:55], off offset:528
	global_load_dwordx4 v[44:47], v[134:135], off offset:512
	global_load_dwordx4 v[48:51], v[134:135], off offset:528
	v_mul_f32_e32 v33, v33, v33
	v_mul_f32_e32 v27, v27, v27
	v_fmac_f32_e32 v31, v30, v30
	v_fmac_f32_e32 v33, v32, v32
	v_mul_f32_e32 v29, v29, v29
	v_fmac_f32_e32 v27, v26, v26
	v_add_f32_e32 v26, v31, v33
	v_fmac_f32_e32 v29, v28, v28
	v_add_f32_e32 v26, v27, v26
	v_add_f32_e32 v26, v29, v26
	s_waitcnt vmcnt(3)
	v_pk_add_f32 v[24:25], v[24:25], v[38:39]
	v_pk_add_f32 v[22:23], v[22:23], v[36:37]
	s_waitcnt vmcnt(2)
	v_pk_add_f32 v[18:19], v[18:19], v[40:41]
	v_mul_f32_e32 v27, v23, v23
	v_mul_f32_e32 v28, v25, v25
	v_pk_add_f32 v[20:21], v[20:21], v[42:43]
	v_mul_f32_e32 v29, v19, v19
	v_fmac_f32_e32 v27, v22, v22
	v_fmac_f32_e32 v28, v24, v24
	v_mul_f32_e32 v30, v21, v21
	v_fmac_f32_e32 v29, v18, v18
	v_add_f32_e32 v27, v27, v28
	v_fmac_f32_e32 v30, v20, v20
	v_add_f32_e32 v27, v29, v27
	v_add_f32_e32 v27, v30, v27
	v_add_f32_e32 v30, v26, v27
	ds_bpermute_b32 v31, v122, v30
	global_store_dwordx4 v[54:55], v[22:25], off offset:512 nt
	global_store_dwordx4 v[54:55], v[18:21], off offset:528 nt
	s_waitcnt vmcnt(2)
	v_pk_mul_f32 v[28:29], v[48:49], v[18:19]
	v_pk_mul_f32 v[22:23], v[44:45], v[22:23]
	v_pk_mul_f32 v[24:25], v[46:47], v[24:25]
	s_waitcnt lgkmcnt(0)
	v_add_f32_e32 v18, v30, v31
	ds_bpermute_b32 v19, v116, v18
	v_pk_mul_f32 v[26:27], v[50:51], v[20:21]
	v_cvt_pk_bf16_f32 v20, v22, v23
	v_cvt_pk_bf16_f32 v21, v24, v25
	v_cvt_pk_bf16_f32 v22, v28, v29
	s_nop 0
	v_cvt_pk_bf16_f32 v23, v26, v27
	global_store_dwordx4 v[52:53], v[20:23], off offset:256
	s_and_saveexec_b64 s[42:43], s[0:1]
	s_cbranch_execz .LBB0_715
	v_lshlrev_b64 v[20:21], 8, v[34:35]
	v_lshl_add_u64 v[20:21], s[38:39], 0, v[20:21]
	v_lshl_add_u64 v[20:21], s[40:41], 2, v[20:21]
	s_lshl_b32 s10, s60, 2
	v_lshl_add_u64 v[20:21], v[20:21], 0, s[10:11]
	s_waitcnt lgkmcnt(0)
	v_add_f32_e32 v18, v18, v19
	global_store_dword v[20:21], v18, off
.LBB0_715:
	s_or_b64 exec, exec, s[42:43]
	v_add_u32_e32 v18, 0xb0, v138
	s_waitcnt lgkmcnt(0)
	v_ashrrev_i32_e32 v19, 31, v18
	v_lshlrev_b64 v[20:21], 12, v[18:19]
	v_lshl_add_u64 v[36:37], v[20:21], 0, v[136:137]
	v_lshl_add_u64 v[38:39], v[36:37], 2, s[26:27]
	global_load_dwordx4 v[20:23], v[38:39], off
	global_load_dwordx4 v[24:27], v[38:39], off offset:16
	global_load_dwordx4 v[28:31], v[134:135], off
	global_load_dwordx4 v[32:35], v[134:135], off offset:16
	v_lshl_add_u64 v[36:37], v[36:37], 1, s[20:21]
	s_waitcnt vmcnt(3)
	v_pk_add_f32 v[16:17], v[16:17], v[22:23]
	v_pk_add_f32 v[14:15], v[14:15], v[20:21]
	s_waitcnt vmcnt(2)
	v_pk_add_f32 v[12:13], v[12:13], v[26:27]
	v_pk_add_f32 v[10:11], v[10:11], v[24:25]
	s_waitcnt vmcnt(1)
	v_pk_mul_f32 v[22:23], v[30:31], v[16:17]
	v_pk_mul_f32 v[20:21], v[28:29], v[14:15]
	global_store_dwordx4 v[38:39], v[14:17], off nt
	global_store_dwordx4 v[38:39], v[10:13], off offset:16 nt
	s_waitcnt vmcnt(2)
	v_pk_mul_f32 v[24:25], v[34:35], v[12:13]
	v_pk_mul_f32 v[26:27], v[32:33], v[10:11]
	v_cvt_pk_bf16_f32 v20, v20, v21
	v_cvt_pk_bf16_f32 v21, v22, v23
	v_mul_f32_e32 v15, v15, v15
	v_cvt_pk_bf16_f32 v22, v26, v27
	v_cvt_pk_bf16_f32 v23, v24, v25
	global_store_dwordx4 v[36:37], v[20:23], off
	global_load_dwordx4 v[20:23], v[38:39], off offset:512
	s_nop 0
	global_load_dwordx4 v[24:27], v[38:39], off offset:528
	global_load_dwordx4 v[28:31], v[134:135], off offset:512
	global_load_dwordx4 v[32:35], v[134:135], off offset:528
	v_mul_f32_e32 v17, v17, v17
	v_mul_f32_e32 v11, v11, v11
	v_fmac_f32_e32 v15, v14, v14
	v_fmac_f32_e32 v17, v16, v16
	v_mul_f32_e32 v13, v13, v13
	v_fmac_f32_e32 v11, v10, v10
	v_add_f32_e32 v10, v15, v17
	v_fmac_f32_e32 v13, v12, v12
	v_add_f32_e32 v10, v11, v10
	v_add_f32_e32 v10, v13, v10
	s_waitcnt vmcnt(3)
	v_pk_add_f32 v[8:9], v[8:9], v[22:23]
	v_pk_add_f32 v[6:7], v[6:7], v[20:21]
	s_waitcnt vmcnt(2)
	v_pk_add_f32 v[2:3], v[2:3], v[24:25]
	v_mul_f32_e32 v11, v7, v7
	v_mul_f32_e32 v12, v9, v9
	v_pk_add_f32 v[4:5], v[4:5], v[26:27]
	v_mul_f32_e32 v13, v3, v3
	v_fmac_f32_e32 v11, v6, v6
	v_fmac_f32_e32 v12, v8, v8
	v_mul_f32_e32 v14, v5, v5
	v_fmac_f32_e32 v13, v2, v2
	v_add_f32_e32 v11, v11, v12
	v_fmac_f32_e32 v14, v4, v4
	v_add_f32_e32 v11, v13, v11
	v_add_f32_e32 v11, v14, v11
	v_add_f32_e32 v14, v10, v11
	ds_bpermute_b32 v15, v122, v14
	global_store_dwordx4 v[38:39], v[6:9], off offset:512 nt
	global_store_dwordx4 v[38:39], v[2:5], off offset:528 nt
	s_waitcnt vmcnt(2)
	v_pk_mul_f32 v[12:13], v[32:33], v[2:3]
	v_pk_mul_f32 v[6:7], v[28:29], v[6:7]
	v_pk_mul_f32 v[8:9], v[30:31], v[8:9]
	s_waitcnt lgkmcnt(0)
	v_add_f32_e32 v2, v14, v15
	ds_bpermute_b32 v3, v116, v2
	v_pk_mul_f32 v[10:11], v[34:35], v[4:5]
	v_cvt_pk_bf16_f32 v4, v6, v7
	v_cvt_pk_bf16_f32 v5, v8, v9
	v_cvt_pk_bf16_f32 v6, v12, v13
	s_nop 0
	v_cvt_pk_bf16_f32 v7, v10, v11
	global_store_dwordx4 v[36:37], v[4:7], off offset:256
	s_and_saveexec_b64 s[42:43], s[0:1]
	s_cbranch_execz .LBB0_717
	v_lshlrev_b64 v[4:5], 8, v[18:19]
	v_lshl_add_u64 v[4:5], s[38:39], 0, v[4:5]
	v_lshl_add_u64 v[4:5], s[40:41], 2, v[4:5]
	s_lshl_b32 s10, s60, 2
	v_lshl_add_u64 v[4:5], v[4:5], 0, s[10:11]
	s_waitcnt lgkmcnt(0)
	v_add_f32_e32 v2, v2, v3
	global_store_dword v[4:5], v2, off
